# GEMM K-loops: first 6 MFMAs of every MMA segment issued before the segment's barrier
# speedup vs baseline: 1.0199x; 1.0018x over previous
; #define PG8_STAGE(bufoff, gbase, voff) do { _Pragma("unroll") for (int _i = 0; _i < 2; ++_i) \
;         __builtin_amdgcn_global_load_lds((const unsigned*)((const char*)(gbase) + (voff)[_i]), (PG8_LAS unsigned*)(lds + (bufoff) + ldsw + _i * 8192), 16, 0, 0); } while (0)
; #define PG8_LDA(dst, b, h) do { _Pragma("unroll") for (int m = 0; m < 4; ++m) _Pragma("unroll") for (int k = 0; k < 2; ++k) dst[m][k] = *(const PG8_LAS bf16x8*)(lds + PG8_SA(b, h) + aoff + m * 2048 + k * 1024); } while (0)
; #define PG8_LDB(dst, b, h) do { _Pragma("unroll") for (int n = 0; n < 2; ++n) _Pragma("unroll") for (int k = 0; k < 2; ++k) dst[n][k] = *(const PG8_LAS bf16x8*)(lds + PG8_SB(b, h) + boff + n * 2048 + k * 1024); } while (0)
; #define PG8_MMA(ai, bj, At, Bt) do { __builtin_amdgcn_s_setprio(1); _Pragma("unroll") for (int m = 0; m < 4; ++m) _Pragma("unroll") for (int n = 0; n < 2; ++n) _Pragma("unroll") for (int k = 0; k < 2; ++k) \
;         acc[ai][bj][m][n] = __builtin_amdgcn_mfma_f32_16x16x32_bf16(Bt[n][k], At[m][k], acc[ai][bj][m][n], 0, 0, 0); __builtin_amdgcn_s_setprio(0); } while (0)
; #define PG8_WAIT_V(n) asm volatile("s_waitcnt vmcnt(" #n ")" ::: "memory")
; #define PG8_WAIT_L(n) asm volatile("s_waitcnt lgkmcnt(" #n ")" ::: "memory")
; template <class Epi, class Sched, bool ALIGN_EPI = false, bool SP2 = false>
; __device__ __forceinline__ void gemm_phase(PG8_LAS unsigned char* lds, const Gemm g, const Sched& S, const Epi& E) {
;     ...
;             const bool last = (t == nt - 2);
;             const char* a1 = cA + (size_t)(t + 1) * kstep;
;             const char* a2 = last ? nA : cA + (size_t)(t + 2) * kstep; const char* b2 = last ? nB : cB + (size_t)(t + 2) * kstep;
;             const char* a3 = a2 + kstep; const char* b3 = b2 + kstep;
;             if (last && has_next) S.a_ready(nxt);
;             if constexpr (SP2) {
;             PG8_LDB(B0, 0, 0); PG8_LDB(B1, 0, 1); PG8_SCHED; PG8_LDA(At, 0, 0); PG8_STAGE(PG8_SA(1, 1), a1 + hstep, voffA);
;             PG8_WAIT_V(8); PG8_WAIT_L(0); PG8_BAR; PG8_MMA(0, 0, At, B0); PG8_MMA(0, 1, At, B1); PG8_BAR; PG8_SCHED;
;             PG8_LDA(At, 0, 1); PG8_STAGE(PG8_SB(0, 0), b2, voffB); PG8_STAGE(PG8_SB(0, 1), b2 + hstep, voffB); PG8_STAGE(PG8_SA(0, 0), a2, voffA);
;             PG8_WAIT_V(8); PG8_WAIT_L(0); PG8_BAR; PG8_MMA(1, 0, At, B0); PG8_MMA(1, 1, At, B1); PG8_BAR; PG8_SCHED;
.LBB0_102:
	ds_read_b128 v[146:149], v152
	ds_read_b128 v[156:159], v152 offset:1024
	ds_read_b128 v[160:163], v152 offset:2048
	ds_read_b128 v[164:167], v152 offset:3072
	ds_read_b128 v[172:175], v153
	ds_read_b128 v[176:179], v153 offset:1024
	ds_read_b128 v[180:183], v153 offset:2048
	ds_read_b128 v[184:187], v153 offset:3072
	s_add_u32 s2, s28, 0xfffc0080
	s_addc_u32 s3, s29, -1
	s_cmp_eq_u32 s46, 12
	s_cselect_b32 s17, s19, s3
	s_cselect_b32 s16, s44, s2
	s_cselect_b32 s3, s15, s31
	s_cselect_b32 s2, s45, s30
	v_lshl_add_u64 v[222:223], s[28:29], 0, v[138:139]
	s_add_i32 m0, s25, 0xc000
	ds_read_b128 v[188:191], v154
	ds_read_b128 v[192:195], v154 offset:1024
	ds_read_b128 v[198:201], v154 offset:2048
	ds_read_b128 v[202:205], v154 offset:3072
	ds_read_b128 v[206:209], v154 offset:4096
	ds_read_b128 v[210:213], v154 offset:5120
	ds_read_b128 v[214:217], v154 offset:6144
	ds_read_b128 v[218:221], v154 offset:7168
	global_load_lds_dwordx4 v[222:223], off
	v_lshl_add_u64 v[222:223], s[28:29], 0, v[140:141]
	s_add_i32 m0, s25, 0xe000
	s_nop 0
	global_load_lds_dwordx4 v[222:223], off
	s_waitcnt vmcnt(8)
	s_waitcnt lgkmcnt(0)
	v_mfma_f32_16x16x32_bf16 v[126:129], v[146:149], v[188:191], v[126:129]
	v_mfma_f32_16x16x32_bf16 v[118:121], v[160:163], v[188:191], v[118:121]
	v_mfma_f32_16x16x32_bf16 v[110:113], v[146:149], v[198:201], v[110:113]
	v_mfma_f32_16x16x32_bf16 v[102:105], v[160:163], v[198:201], v[102:105]
	v_mfma_f32_16x16x32_bf16 v[94:97], v[146:149], v[206:209], v[94:97]
	v_mfma_f32_16x16x32_bf16 v[86:89], v[160:163], v[206:209], v[86:89]
	s_barrier
	s_setprio 1
	s_waitcnt lgkmcnt(0)
	v_mfma_f32_16x16x32_bf16 v[78:81], v[146:149], v[214:217], v[78:81]
	v_mfma_f32_16x16x32_bf16 v[70:73], v[160:163], v[214:217], v[70:73]
	v_mfma_f32_16x16x32_bf16 v[126:129], v[156:159], v[192:195], v[126:129]
	v_mfma_f32_16x16x32_bf16 v[118:121], v[164:167], v[192:195], v[118:121]
	v_mfma_f32_16x16x32_bf16 v[110:113], v[156:159], v[202:205], v[110:113]
	v_mfma_f32_16x16x32_bf16 v[102:105], v[164:167], v[202:205], v[102:105]
	v_mfma_f32_16x16x32_bf16 v[94:97], v[156:159], v[210:213], v[94:97]
	v_mfma_f32_16x16x32_bf16 v[86:89], v[164:167], v[210:213], v[86:89]
	v_mfma_f32_16x16x32_bf16 v[78:81], v[156:159], v[218:221], v[78:81]
	v_mfma_f32_16x16x32_bf16 v[70:73], v[164:167], v[218:221], v[70:73]
	s_setprio 0
	s_setprio 1
	v_mfma_f32_16x16x32_bf16 v[122:125], v[172:175], v[188:191], v[122:125]
	v_mfma_f32_16x16x32_bf16 v[114:117], v[180:183], v[188:191], v[114:117]
	v_mfma_f32_16x16x32_bf16 v[106:109], v[172:175], v[198:201], v[106:109]
	v_mfma_f32_16x16x32_bf16 v[98:101], v[180:183], v[198:201], v[98:101]
	v_mfma_f32_16x16x32_bf16 v[90:93], v[172:175], v[206:209], v[90:93]
	v_mfma_f32_16x16x32_bf16 v[82:85], v[180:183], v[206:209], v[82:85]
	v_mfma_f32_16x16x32_bf16 v[74:77], v[172:175], v[214:217], v[74:77]
	v_mfma_f32_16x16x32_bf16 v[66:69], v[180:183], v[214:217], v[66:69]
	v_mfma_f32_16x16x32_bf16 v[122:125], v[176:179], v[192:195], v[122:125]
	v_mfma_f32_16x16x32_bf16 v[114:117], v[184:187], v[192:195], v[114:117]
	v_mfma_f32_16x16x32_bf16 v[106:109], v[176:179], v[202:205], v[106:109]
	v_mfma_f32_16x16x32_bf16 v[98:101], v[184:187], v[202:205], v[98:101]
	v_mfma_f32_16x16x32_bf16 v[90:93], v[176:179], v[210:213], v[90:93]
	v_mfma_f32_16x16x32_bf16 v[82:85], v[184:187], v[210:213], v[82:85]
	v_mfma_f32_16x16x32_bf16 v[74:77], v[176:179], v[218:221], v[74:77]
	v_mfma_f32_16x16x32_bf16 v[66:69], v[184:187], v[218:221], v[66:69]
	s_setprio 0
	s_barrier
	s_add_i32 s47, s40, s27
	v_lshl_add_u64 v[222:223], s[2:3], 0, v[132:133]
	s_mov_b32 m0, s47
	ds_read_b128 v[188:191], v154 offset:16384
	ds_read_b128 v[192:195], v154 offset:17408
	ds_read_b128 v[198:201], v154 offset:18432
	ds_read_b128 v[202:205], v154 offset:19456
	ds_read_b128 v[206:209], v154 offset:20480
	ds_read_b128 v[210:213], v154 offset:21504
	ds_read_b128 v[214:217], v154 offset:22528
	ds_read_b128 v[218:221], v154 offset:23552
	global_load_lds_dwordx4 v[222:223], off
	s_add_i32 m0, s47, 0x2000
	s_add_u32 s48, s2, 0x40000
	v_lshl_add_u64 v[224:225], s[2:3], 0, v[136:137]
	s_addc_u32 s49, s3, 0
	s_add_i32 s47, s41, s27
	global_load_lds_dwordx4 v[224:225], off
	v_lshl_add_u64 v[226:227], s[48:49], 0, v[132:133]
	s_mov_b32 m0, s47
	v_lshl_add_u64 v[228:229], s[16:17], 0, v[134:135]
	global_load_lds_dwordx4 v[226:227], off
	v_lshl_add_u64 v[226:227], s[48:49], 0, v[136:137]
	s_add_i32 m0, s47, 0x2000
	s_nop 0
	global_load_lds_dwordx4 v[226:227], off
	v_lshl_add_u64 v[226:227], s[16:17], 0, v[130:131]
	s_mov_b32 m0, s25
	s_nop 0
	global_load_lds_dwordx4 v[226:227], off
	s_mov_b32 m0, s33
	s_nop 0
	global_load_lds_dwordx4 v[228:229], off
	s_waitcnt vmcnt(8)
	s_waitcnt lgkmcnt(0)
	v_mfma_f32_16x16x32_bf16 v[62:65], v[146:149], v[188:191], v[62:65]
	v_mfma_f32_16x16x32_bf16 v[54:57], v[160:163], v[188:191], v[54:57]
	v_mfma_f32_16x16x32_bf16 v[46:49], v[146:149], v[198:201], v[46:49]
	v_mfma_f32_16x16x32_bf16 v[38:41], v[160:163], v[198:201], v[38:41]
	v_mfma_f32_16x16x32_bf16 v[30:33], v[146:149], v[206:209], v[30:33]
	v_mfma_f32_16x16x32_bf16 v[22:25], v[160:163], v[206:209], v[22:25]
	s_barrier
; #define PG8_STAGE(bufoff, gbase, voff) do { _Pragma("unroll") for (int _i = 0; _i < 2; ++_i) \
;         __builtin_amdgcn_global_load_lds((const unsigned*)((const char*)(gbase) + (voff)[_i]), (PG8_LAS unsigned*)(lds + (bufoff) + ldsw + _i * 8192), 16, 0, 0); } while (0)
; #define PG8_LDA(dst, b, h) do { _Pragma("unroll") for (int m = 0; m < 4; ++m) _Pragma("unroll") for (int k = 0; k < 2; ++k) dst[m][k] = *(const PG8_LAS bf16x8*)(lds + PG8_SA(b, h) + aoff + m * 2048 + k * 1024); } while (0)
; #define PG8_LDB(dst, b, h) do { _Pragma("unroll") for (int n = 0; n < 2; ++n) _Pragma("unroll") for (int k = 0; k < 2; ++k) dst[n][k] = *(const PG8_LAS bf16x8*)(lds + PG8_SB(b, h) + boff + n * 2048 + k * 1024); } while (0)
; #define PG8_MMA(ai, bj, At, Bt) do { __builtin_amdgcn_s_setprio(1); _Pragma("unroll") for (int m = 0; m < 4; ++m) _Pragma("unroll") for (int n = 0; n < 2; ++n) _Pragma("unroll") for (int k = 0; k < 2; ++k) \
;         acc[ai][bj][m][n] = __builtin_amdgcn_mfma_f32_16x16x32_bf16(Bt[n][k], At[m][k], acc[ai][bj][m][n], 0, 0, 0); __builtin_amdgcn_s_setprio(0); } while (0)
; #define PG8_WAIT_V(n) asm volatile("s_waitcnt vmcnt(" #n ")" ::: "memory")
; #define PG8_WAIT_L(n) asm volatile("s_waitcnt lgkmcnt(" #n ")" ::: "memory")
; #define PG8_BAR __builtin_amdgcn_s_barrier()
; #define PG8_SCHED __builtin_amdgcn_sched_barrier(0)
; template <class Epi, class Sched, bool ALIGN_EPI = false, bool SP2 = false>
; __device__ __forceinline__ void gemm_phase(PG8_LAS unsigned char* lds, const Gemm g, const Sched& S, const Epi& E) {
;     ...
;             PG8_WAIT_V(8); PG8_WAIT_L(0); PG8_BAR; PG8_MMA(1, 0, At, B0); PG8_MMA(1, 1, At, B1); PG8_BAR; PG8_SCHED;
;             PG8_LDB(B0, 1, 0); PG8_LDB(B1, 1, 1); PG8_SCHED; PG8_LDA(At, 1, 0); PG8_STAGE(PG8_SA(0, 1), a2 + hstep, voffA);
;             PG8_WAIT_V(8); PG8_WAIT_L(0); PG8_BAR; PG8_MMA(0, 0, At, B0); PG8_MMA(0, 1, At, B1); PG8_BAR; PG8_SCHED;
	s_setprio 1
	s_waitcnt lgkmcnt(0)
	v_mfma_f32_16x16x32_bf16 v[14:17], v[146:149], v[214:217], v[14:17]
	v_mfma_f32_16x16x32_bf16 v[6:9], v[160:163], v[214:217], v[6:9]
	v_mfma_f32_16x16x32_bf16 v[62:65], v[156:159], v[192:195], v[62:65]
	v_mfma_f32_16x16x32_bf16 v[54:57], v[164:167], v[192:195], v[54:57]
	v_mfma_f32_16x16x32_bf16 v[46:49], v[156:159], v[202:205], v[46:49]
	v_mfma_f32_16x16x32_bf16 v[38:41], v[164:167], v[202:205], v[38:41]
	v_mfma_f32_16x16x32_bf16 v[30:33], v[156:159], v[210:213], v[30:33]
	v_mfma_f32_16x16x32_bf16 v[22:25], v[164:167], v[210:213], v[22:25]
	v_mfma_f32_16x16x32_bf16 v[14:17], v[156:159], v[218:221], v[14:17]
	v_mfma_f32_16x16x32_bf16 v[6:9], v[164:167], v[218:221], v[6:9]
	s_setprio 0
	s_setprio 1
	v_mfma_f32_16x16x32_bf16 v[58:61], v[172:175], v[188:191], v[58:61]
	v_mfma_f32_16x16x32_bf16 v[50:53], v[180:183], v[188:191], v[50:53]
	v_mfma_f32_16x16x32_bf16 v[42:45], v[172:175], v[198:201], v[42:45]
	v_mfma_f32_16x16x32_bf16 v[34:37], v[180:183], v[198:201], v[34:37]
	v_mfma_f32_16x16x32_bf16 v[26:29], v[172:175], v[206:209], v[26:29]
	v_mfma_f32_16x16x32_bf16 v[18:21], v[180:183], v[206:209], v[18:21]
	v_mfma_f32_16x16x32_bf16 v[10:13], v[172:175], v[214:217], v[10:13]
	v_mfma_f32_16x16x32_bf16 v[2:5], v[180:183], v[214:217], v[2:5]
	v_mfma_f32_16x16x32_bf16 v[58:61], v[176:179], v[192:195], v[58:61]
	v_mfma_f32_16x16x32_bf16 v[50:53], v[184:187], v[192:195], v[50:53]
	v_mfma_f32_16x16x32_bf16 v[42:45], v[176:179], v[202:205], v[42:45]
	v_mfma_f32_16x16x32_bf16 v[34:37], v[184:187], v[202:205], v[34:37]
	v_mfma_f32_16x16x32_bf16 v[26:29], v[176:179], v[210:213], v[26:29]
	v_mfma_f32_16x16x32_bf16 v[18:21], v[184:187], v[210:213], v[18:21]
	v_mfma_f32_16x16x32_bf16 v[10:13], v[176:179], v[218:221], v[10:13]
	v_mfma_f32_16x16x32_bf16 v[2:5], v[184:187], v[218:221], v[2:5]
	s_setprio 0
	s_barrier
	s_add_i32 s47, 0, 0x18000
	v_add_u32_e32 v155, s47, v150
	s_add_i32 s48, 0, 0x1c000
	ds_read_b128 v[146:149], v155
	ds_read_b128 v[156:159], v155 offset:1024
	ds_read_b128 v[160:163], v155 offset:2048
	ds_read_b128 v[164:167], v155 offset:3072
	v_add_u32_e32 v155, s48, v150
	ds_read_b128 v[172:175], v155
	ds_read_b128 v[176:179], v155 offset:1024
	ds_read_b128 v[180:183], v155 offset:2048
	ds_read_b128 v[184:187], v155 offset:3072
	s_add_u32 s16, s16, 0x40000
	s_addc_u32 s17, s17, 0
	s_mov_b32 m0, s34
	v_lshl_add_u64 v[230:231], s[16:17], 0, v[130:131]
	ds_read_b128 v[188:191], v154 offset:32768
	ds_read_b128 v[192:195], v154 offset:33792
	ds_read_b128 v[198:201], v154 offset:34816
	ds_read_b128 v[202:205], v154 offset:35840
	ds_read_b128 v[206:209], v154 offset:36864
	ds_read_b128 v[210:213], v154 offset:37888
	ds_read_b128 v[214:217], v154 offset:38912
	ds_read_b128 v[218:221], v154 offset:39936
	global_load_lds_dwordx4 v[230:231], off
	v_lshl_add_u64 v[230:231], s[16:17], 0, v[134:135]
	s_mov_b32 m0, s35
	s_nop 0
	global_load_lds_dwordx4 v[230:231], off
	s_waitcnt vmcnt(8)
	s_waitcnt lgkmcnt(0)
	v_mfma_f32_16x16x32_bf16 v[126:129], v[146:149], v[188:191], v[126:129]
	v_mfma_f32_16x16x32_bf16 v[118:121], v[160:163], v[188:191], v[118:121]
	v_mfma_f32_16x16x32_bf16 v[110:113], v[146:149], v[198:201], v[110:113]
	v_mfma_f32_16x16x32_bf16 v[102:105], v[160:163], v[198:201], v[102:105]
	v_mfma_f32_16x16x32_bf16 v[94:97], v[146:149], v[206:209], v[94:97]
	v_mfma_f32_16x16x32_bf16 v[86:89], v[160:163], v[206:209], v[86:89]
	s_barrier
	s_setprio 1
	s_waitcnt lgkmcnt(0)
	v_mfma_f32_16x16x32_bf16 v[78:81], v[146:149], v[214:217], v[78:81]
	v_mfma_f32_16x16x32_bf16 v[70:73], v[160:163], v[214:217], v[70:73]
	v_mfma_f32_16x16x32_bf16 v[126:129], v[156:159], v[192:195], v[126:129]
	v_mfma_f32_16x16x32_bf16 v[118:121], v[164:167], v[192:195], v[118:121]
	v_mfma_f32_16x16x32_bf16 v[110:113], v[156:159], v[202:205], v[110:113]
	v_mfma_f32_16x16x32_bf16 v[102:105], v[164:167], v[202:205], v[102:105]
	v_mfma_f32_16x16x32_bf16 v[94:97], v[156:159], v[210:213], v[94:97]
	v_mfma_f32_16x16x32_bf16 v[86:89], v[164:167], v[210:213], v[86:89]
	v_mfma_f32_16x16x32_bf16 v[78:81], v[156:159], v[218:221], v[78:81]
	v_mfma_f32_16x16x32_bf16 v[70:73], v[164:167], v[218:221], v[70:73]
	s_setprio 0
	s_setprio 1
	v_mfma_f32_16x16x32_bf16 v[122:125], v[172:175], v[188:191], v[122:125]
	v_mfma_f32_16x16x32_bf16 v[114:117], v[180:183], v[188:191], v[114:117]
	v_mfma_f32_16x16x32_bf16 v[106:109], v[172:175], v[198:201], v[106:109]
	v_mfma_f32_16x16x32_bf16 v[98:101], v[180:183], v[198:201], v[98:101]
	v_mfma_f32_16x16x32_bf16 v[90:93], v[172:175], v[206:209], v[90:93]
	v_mfma_f32_16x16x32_bf16 v[82:85], v[180:183], v[206:209], v[82:85]
	v_mfma_f32_16x16x32_bf16 v[74:77], v[172:175], v[214:217], v[74:77]
	v_mfma_f32_16x16x32_bf16 v[66:69], v[180:183], v[214:217], v[66:69]
	v_mfma_f32_16x16x32_bf16 v[122:125], v[176:179], v[192:195], v[122:125]
	v_mfma_f32_16x16x32_bf16 v[114:117], v[184:187], v[192:195], v[114:117]
	v_mfma_f32_16x16x32_bf16 v[106:109], v[176:179], v[202:205], v[106:109]
	v_mfma_f32_16x16x32_bf16 v[98:101], v[184:187], v[202:205], v[98:101]
	v_mfma_f32_16x16x32_bf16 v[90:93], v[176:179], v[210:213], v[90:93]
	v_mfma_f32_16x16x32_bf16 v[82:85], v[184:187], v[210:213], v[82:85]
	v_mfma_f32_16x16x32_bf16 v[74:77], v[176:179], v[218:221], v[74:77]
	v_mfma_f32_16x16x32_bf16 v[66:69], v[184:187], v[218:221], v[66:69]
	s_setprio 0
	s_barrier
; #define PG8_STAGE(bufoff, gbase, voff) do { _Pragma("unroll") for (int _i = 0; _i < 2; ++_i) \
;         __builtin_amdgcn_global_load_lds((const unsigned*)((const char*)(gbase) + (voff)[_i]), (PG8_LAS unsigned*)(lds + (bufoff) + ldsw + _i * 8192), 16, 0, 0); } while (0)
; #define PG8_LDA(dst, b, h) do { _Pragma("unroll") for (int m = 0; m < 4; ++m) _Pragma("unroll") for (int k = 0; k < 2; ++k) dst[m][k] = *(const PG8_LAS bf16x8*)(lds + PG8_SA(b, h) + aoff + m * 2048 + k * 1024); } while (0)
; #define PG8_MMA(ai, bj, At, Bt) do { __builtin_amdgcn_s_setprio(1); _Pragma("unroll") for (int m = 0; m < 4; ++m) _Pragma("unroll") for (int n = 0; n < 2; ++n) _Pragma("unroll") for (int k = 0; k < 2; ++k) \
;         acc[ai][bj][m][n] = __builtin_amdgcn_mfma_f32_16x16x32_bf16(Bt[n][k], At[m][k], acc[ai][bj][m][n], 0, 0, 0); __builtin_amdgcn_s_setprio(0); } while (0)
; #define PG8_WAIT_V(n) asm volatile("s_waitcnt vmcnt(" #n ")" ::: "memory")
; #define PG8_WAIT_L(n) asm volatile("s_waitcnt lgkmcnt(" #n ")" ::: "memory")
; #define PG8_BAR __builtin_amdgcn_s_barrier()
; #define PG8_SCHED __builtin_amdgcn_sched_barrier(0)
; template <class Epi, class Sched, bool ALIGN_EPI = false, bool SP2 = false>
; __device__ __forceinline__ void gemm_phase(PG8_LAS unsigned char* lds, const Gemm g, const Sched& S, const Epi& E) {
;     ...
;             PG8_LDA(At, 1, 1); PG8_STAGE(PG8_SB(1, 0), b3, voffB); PG8_STAGE(PG8_SB(1, 1), b3 + hstep, voffB); PG8_STAGE(PG8_SA(1, 0), a3, voffA);
;             PG8_WAIT_V(8); PG8_WAIT_L(0); PG8_BAR; PG8_MMA(1, 0, At, B0); PG8_MMA(1, 1, At, B1); PG8_BAR; PG8_SCHED;
;     ...
;         if constexpr (ALIGN_EPI) { if (wr == 0) PG8_BAR; }
	s_add_i32 s16, s47, s27
	v_lshl_add_u64 v[222:223], v[222:223], 0, s[6:7]
	s_mov_b32 m0, s16
	ds_read_b128 v[188:191], v154 offset:49152
	ds_read_b128 v[192:195], v154 offset:50176
	ds_read_b128 v[198:201], v154 offset:51200
	ds_read_b128 v[202:205], v154 offset:52224
	ds_read_b128 v[206:209], v154 offset:53248
	ds_read_b128 v[210:213], v154 offset:54272
	ds_read_b128 v[214:217], v154 offset:55296
	ds_read_b128 v[218:221], v154 offset:56320
	global_load_lds_dwordx4 v[222:223], off
	s_add_i32 m0, s16, 0x2000
	s_add_u32 s2, s2, 0x40080
	v_lshl_add_u64 v[222:223], v[224:225], 0, s[6:7]
	s_addc_u32 s3, s3, 0
	s_add_i32 s16, s48, s27
	global_load_lds_dwordx4 v[222:223], off
	v_lshl_add_u64 v[222:223], s[2:3], 0, v[132:133]
	s_mov_b32 m0, s16
	s_nop 0
	global_load_lds_dwordx4 v[222:223], off
	v_lshl_add_u64 v[222:223], s[2:3], 0, v[136:137]
	s_add_i32 m0, s16, 0x2000
	s_nop 0
	global_load_lds_dwordx4 v[222:223], off
	v_lshl_add_u64 v[222:223], v[226:227], 0, s[6:7]
	s_mov_b32 m0, s37
	s_nop 0
	global_load_lds_dwordx4 v[222:223], off
	v_lshl_add_u64 v[222:223], v[228:229], 0, s[6:7]
	s_mov_b32 m0, s38
	s_nop 0
	global_load_lds_dwordx4 v[222:223], off
	s_waitcnt vmcnt(8)
	s_waitcnt lgkmcnt(0)
	v_mfma_f32_16x16x32_bf16 v[62:65], v[146:149], v[188:191], v[62:65]
	v_mfma_f32_16x16x32_bf16 v[54:57], v[160:163], v[188:191], v[54:57]
	v_mfma_f32_16x16x32_bf16 v[46:49], v[146:149], v[198:201], v[46:49]
	v_mfma_f32_16x16x32_bf16 v[38:41], v[160:163], v[198:201], v[38:41]
	v_mfma_f32_16x16x32_bf16 v[30:33], v[146:149], v[206:209], v[30:33]
	v_mfma_f32_16x16x32_bf16 v[22:25], v[160:163], v[206:209], v[22:25]
	s_barrier
	s_setprio 1
	s_waitcnt lgkmcnt(0)
	v_mfma_f32_16x16x32_bf16 v[14:17], v[146:149], v[214:217], v[14:17]
	v_mfma_f32_16x16x32_bf16 v[6:9], v[160:163], v[214:217], v[6:9]
	v_mfma_f32_16x16x32_bf16 v[62:65], v[156:159], v[192:195], v[62:65]
	v_mfma_f32_16x16x32_bf16 v[54:57], v[164:167], v[192:195], v[54:57]
	v_mfma_f32_16x16x32_bf16 v[46:49], v[156:159], v[202:205], v[46:49]
	v_mfma_f32_16x16x32_bf16 v[38:41], v[164:167], v[202:205], v[38:41]
	v_mfma_f32_16x16x32_bf16 v[30:33], v[156:159], v[210:213], v[30:33]
	v_mfma_f32_16x16x32_bf16 v[22:25], v[164:167], v[210:213], v[22:25]
	v_mfma_f32_16x16x32_bf16 v[14:17], v[156:159], v[218:221], v[14:17]
	v_mfma_f32_16x16x32_bf16 v[6:9], v[164:167], v[218:221], v[6:9]
	s_setprio 0
	s_setprio 1
	v_mfma_f32_16x16x32_bf16 v[58:61], v[172:175], v[188:191], v[58:61]
	v_mfma_f32_16x16x32_bf16 v[50:53], v[180:183], v[188:191], v[50:53]
	v_mfma_f32_16x16x32_bf16 v[42:45], v[172:175], v[198:201], v[42:45]
	v_mfma_f32_16x16x32_bf16 v[34:37], v[180:183], v[198:201], v[34:37]
	v_mfma_f32_16x16x32_bf16 v[26:29], v[172:175], v[206:209], v[26:29]
	v_mfma_f32_16x16x32_bf16 v[18:21], v[180:183], v[206:209], v[18:21]
	v_mfma_f32_16x16x32_bf16 v[10:13], v[172:175], v[214:217], v[10:13]
	v_mfma_f32_16x16x32_bf16 v[2:5], v[180:183], v[214:217], v[2:5]
	v_mfma_f32_16x16x32_bf16 v[58:61], v[176:179], v[192:195], v[58:61]
	v_mfma_f32_16x16x32_bf16 v[50:53], v[184:187], v[192:195], v[50:53]
	v_mfma_f32_16x16x32_bf16 v[42:45], v[176:179], v[202:205], v[42:45]
	v_mfma_f32_16x16x32_bf16 v[34:37], v[184:187], v[202:205], v[34:37]
	v_mfma_f32_16x16x32_bf16 v[26:29], v[176:179], v[210:213], v[26:29]
	v_mfma_f32_16x16x32_bf16 v[18:21], v[184:187], v[210:213], v[18:21]
	v_mfma_f32_16x16x32_bf16 v[10:13], v[176:179], v[218:221], v[10:13]
	v_mfma_f32_16x16x32_bf16 v[2:5], v[184:187], v[218:221], v[2:5]
	s_setprio 0
	s_barrier
	s_add_i32 s46, s46, 2
	s_add_u32 s28, s28, 0x100
	s_addc_u32 s29, s29, 0
	s_add_u32 s30, s30, 0x100
	s_addc_u32 s31, s31, 0
	s_cmp_gt_u32 s46, 13
	s_cbranch_scc0 .LBB0_102
	s_and_b64 vcc, exec, s[12:13]
	s_cbranch_vccz .LBB0_105
	s_barrier

; #define PG8_STAGE(bufoff, gbase, voff) do { _Pragma("unroll") for (int _i = 0; _i < 2; ++_i) \
;         __builtin_amdgcn_global_load_lds((const unsigned*)((const char*)(gbase) + (voff)[_i]), (PG8_LAS unsigned*)(lds + (bufoff) + ldsw + _i * 8192), 16, 0, 0); } while (0)
; #define PG8_LDA(dst, b, h) do { _Pragma("unroll") for (int m = 0; m < 4; ++m) _Pragma("unroll") for (int k = 0; k < 2; ++k) dst[m][k] = *(const PG8_LAS bf16x8*)(lds + PG8_SA(b, h) + aoff + m * 2048 + k * 1024); } while (0)
; #define PG8_LDB(dst, b, h) do { _Pragma("unroll") for (int n = 0; n < 2; ++n) _Pragma("unroll") for (int k = 0; k < 2; ++k) dst[n][k] = *(const PG8_LAS bf16x8*)(lds + PG8_SB(b, h) + boff + n * 2048 + k * 1024); } while (0)
; #define PG8_MMA(ai, bj, At, Bt) do { __builtin_amdgcn_s_setprio(1); _Pragma("unroll") for (int m = 0; m < 4; ++m) _Pragma("unroll") for (int n = 0; n < 2; ++n) _Pragma("unroll") for (int k = 0; k < 2; ++k) \
;         acc[ai][bj][m][n] = __builtin_amdgcn_mfma_f32_16x16x32_bf16(Bt[n][k], At[m][k], acc[ai][bj][m][n], 0, 0, 0); __builtin_amdgcn_s_setprio(0); } while (0)
; #define PG8_WAIT_V(n) asm volatile("s_waitcnt vmcnt(" #n ")" ::: "memory")
; #define PG8_WAIT_L(n) asm volatile("s_waitcnt lgkmcnt(" #n ")" ::: "memory")
; template <class Epi, class Sched, bool ALIGN_EPI = false, bool SP2 = false>
; __device__ __forceinline__ void gemm_phase(PG8_LAS unsigned char* lds, const Gemm g, const Sched& S, const Epi& E) {
;     ...
;             const bool last = (t == nt - 2);
;             const char* a1 = cA + (size_t)(t + 1) * kstep;
;             const char* a2 = last ? nA : cA + (size_t)(t + 2) * kstep; const char* b2 = last ? nB : cB + (size_t)(t + 2) * kstep;
;             const char* a3 = a2 + kstep; const char* b3 = b2 + kstep;
;             if (last && has_next) S.a_ready(nxt);
;             if constexpr (SP2) {
;             PG8_LDB(B0, 0, 0); PG8_LDB(B1, 0, 1); PG8_SCHED; PG8_LDA(At, 0, 0); PG8_STAGE(PG8_SA(1, 1), a1 + hstep, voffA);
;             PG8_WAIT_V(8); PG8_WAIT_L(0); PG8_BAR; PG8_MMA(0, 0, At, B0); PG8_MMA(0, 1, At, B1); PG8_BAR; PG8_SCHED;
;             PG8_LDA(At, 0, 1); PG8_STAGE(PG8_SB(0, 0), b2, voffB); PG8_STAGE(PG8_SB(0, 1), b2 + hstep, voffB); PG8_STAGE(PG8_SA(0, 0), a2, voffA);
;             PG8_WAIT_V(8); PG8_WAIT_L(0); PG8_BAR; PG8_MMA(1, 0, At, B0); PG8_MMA(1, 1, At, B1); PG8_BAR; PG8_SCHED;
.LBB0_187:
	v_add_u32_e32 v155, s40, v153
	ds_read_b128 v[156:159], v155
	ds_read_b128 v[160:163], v155 offset:1024
	ds_read_b128 v[164:167], v155 offset:2048
	ds_read_b128 v[172:175], v155 offset:3072
	v_add_u32_e32 v155, s41, v153
	s_add_u32 s2, s12, s22
	ds_read_b128 v[176:179], v155
	ds_read_b128 v[180:183], v155 offset:1024
	ds_read_b128 v[184:187], v155 offset:2048
	ds_read_b128 v[188:191], v155 offset:3072
	s_addc_u32 s3, s13, s23
	s_add_u32 s2, s2, 0x100
	s_addc_u32 s3, s3, 0
	s_add_u32 s49, s45, s22
	s_addc_u32 s52, s46, s23
	s_cmpk_eq_i32 s22, 0x1500
	s_cselect_b32 s17, s21, s3
	s_cselect_b32 s16, s20, s2
	s_cselect_b32 s3, s1, s52
	s_cselect_b32 s2, s0, s49
	v_lshl_add_u64 v[226:227], v[148:149], 0, s[22:23]
	s_add_i32 m0, s30, 0xc000
	ds_read_b128 v[192:195], v154
	ds_read_b128 v[198:201], v154 offset:1024
	ds_read_b128 v[202:205], v154 offset:2048
	ds_read_b128 v[206:209], v154 offset:3072
	ds_read_b128 v[210:213], v154 offset:4096
	ds_read_b128 v[214:217], v154 offset:5120
	ds_read_b128 v[218:221], v154 offset:6144
	ds_read_b128 v[222:225], v154 offset:7168
	global_load_lds_dwordx4 v[226:227], off
	v_lshl_add_u64 v[226:227], v[150:151], 0, s[22:23]
	s_add_i32 m0, s30, 0xe000
	s_nop 0
	global_load_lds_dwordx4 v[226:227], off
	s_waitcnt vmcnt(8)
	s_waitcnt lgkmcnt(0)
	v_mfma_f32_16x16x32_bf16 v[112:115], v[156:159], v[192:195], v[112:115]
	v_mfma_f32_16x16x32_bf16 v[124:127], v[164:167], v[192:195], v[124:127]
	v_mfma_f32_16x16x32_bf16 v[96:99], v[156:159], v[202:205], v[96:99]
	v_mfma_f32_16x16x32_bf16 v[128:131], v[164:167], v[202:205], v[128:131]
	v_mfma_f32_16x16x32_bf16 v[100:103], v[156:159], v[210:213], v[100:103]
	v_mfma_f32_16x16x32_bf16 v[116:119], v[164:167], v[210:213], v[116:119]
	s_barrier
	s_setprio 1
	s_waitcnt lgkmcnt(0)
	v_mfma_f32_16x16x32_bf16 v[104:107], v[156:159], v[218:221], v[104:107]
	v_mfma_f32_16x16x32_bf16 v[120:123], v[164:167], v[218:221], v[120:123]
	v_mfma_f32_16x16x32_bf16 v[112:115], v[160:163], v[198:201], v[112:115]
	v_mfma_f32_16x16x32_bf16 v[124:127], v[172:175], v[198:201], v[124:127]
	v_mfma_f32_16x16x32_bf16 v[96:99], v[160:163], v[206:209], v[96:99]
	v_mfma_f32_16x16x32_bf16 v[128:131], v[172:175], v[206:209], v[128:131]
	v_mfma_f32_16x16x32_bf16 v[100:103], v[160:163], v[214:217], v[100:103]
	v_mfma_f32_16x16x32_bf16 v[116:119], v[172:175], v[214:217], v[116:119]
	v_mfma_f32_16x16x32_bf16 v[104:107], v[160:163], v[222:225], v[104:107]
	v_mfma_f32_16x16x32_bf16 v[120:123], v[172:175], v[222:225], v[120:123]
	s_setprio 0
	s_setprio 1
	v_mfma_f32_16x16x32_bf16 v[108:111], v[176:179], v[192:195], v[108:111]
	v_mfma_f32_16x16x32_bf16 v[92:95], v[184:187], v[192:195], v[92:95]
	v_mfma_f32_16x16x32_bf16 v[80:83], v[176:179], v[202:205], v[80:83]
	v_mfma_f32_16x16x32_bf16 v[68:71], v[184:187], v[202:205], v[68:71]
	v_mfma_f32_16x16x32_bf16 v[84:87], v[176:179], v[210:213], v[84:87]
	v_mfma_f32_16x16x32_bf16 v[72:75], v[184:187], v[210:213], v[72:75]
	v_mfma_f32_16x16x32_bf16 v[88:91], v[176:179], v[218:221], v[88:91]
	v_mfma_f32_16x16x32_bf16 v[76:79], v[184:187], v[218:221], v[76:79]
	v_mfma_f32_16x16x32_bf16 v[108:111], v[180:183], v[198:201], v[108:111]
	v_mfma_f32_16x16x32_bf16 v[92:95], v[188:191], v[198:201], v[92:95]
	v_mfma_f32_16x16x32_bf16 v[80:83], v[180:183], v[206:209], v[80:83]
	v_mfma_f32_16x16x32_bf16 v[68:71], v[188:191], v[206:209], v[68:71]
	v_mfma_f32_16x16x32_bf16 v[84:87], v[180:183], v[214:217], v[84:87]
	v_mfma_f32_16x16x32_bf16 v[72:75], v[188:191], v[214:217], v[72:75]
	v_mfma_f32_16x16x32_bf16 v[88:91], v[180:183], v[222:225], v[88:91]
	v_mfma_f32_16x16x32_bf16 v[76:79], v[188:191], v[222:225], v[76:79]
	s_setprio 0
	s_barrier
	s_add_i32 s49, s40, s29
	v_lshl_add_u64 v[226:227], s[2:3], 0, v[134:135]
	s_mov_b32 m0, s49
	ds_read_b128 v[192:195], v154 offset:16384
	ds_read_b128 v[198:201], v154 offset:17408
	ds_read_b128 v[202:205], v154 offset:18432
	ds_read_b128 v[206:209], v154 offset:19456
	ds_read_b128 v[210:213], v154 offset:20480
	ds_read_b128 v[214:217], v154 offset:21504
	ds_read_b128 v[218:221], v154 offset:22528
	ds_read_b128 v[222:225], v154 offset:23552
	global_load_lds_dwordx4 v[226:227], off
	s_add_i32 m0, s49, 0x2000
	s_add_u32 s52, s2, 0xb0000
	v_lshl_add_u64 v[228:229], s[2:3], 0, v[138:139]
	s_addc_u32 s53, s3, 0
	s_add_i32 s49, s41, s29
	global_load_lds_dwordx4 v[228:229], off
	v_lshl_add_u64 v[230:231], s[52:53], 0, v[134:135]
	s_mov_b32 m0, s49
	v_lshl_add_u64 v[232:233], s[16:17], 0, v[136:137]
	global_load_lds_dwordx4 v[230:231], off
	v_lshl_add_u64 v[230:231], s[52:53], 0, v[138:139]
	s_add_i32 m0, s49, 0x2000
	s_nop 0
	global_load_lds_dwordx4 v[230:231], off
	v_lshl_add_u64 v[230:231], s[16:17], 0, v[132:133]
	s_mov_b32 m0, s30
	s_nop 0
	global_load_lds_dwordx4 v[230:231], off
	s_mov_b32 m0, s31
	s_nop 0
	global_load_lds_dwordx4 v[232:233], off
	s_waitcnt vmcnt(8)
	s_waitcnt lgkmcnt(0)
	v_mfma_f32_16x16x32_bf16 v[64:67], v[156:159], v[192:195], v[64:67]
	v_mfma_f32_16x16x32_bf16 v[60:63], v[164:167], v[192:195], v[60:63]
	v_mfma_f32_16x16x32_bf16 v[48:51], v[156:159], v[202:205], v[48:51]
	v_mfma_f32_16x16x32_bf16 v[44:47], v[164:167], v[202:205], v[44:47]
	v_mfma_f32_16x16x32_bf16 v[32:35], v[156:159], v[210:213], v[32:35]
	v_mfma_f32_16x16x32_bf16 v[28:31], v[164:167], v[210:213], v[28:31]
	s_barrier
; #define PG8_STAGE(bufoff, gbase, voff) do { _Pragma("unroll") for (int _i = 0; _i < 2; ++_i) \
;         __builtin_amdgcn_global_load_lds((const unsigned*)((const char*)(gbase) + (voff)[_i]), (PG8_LAS unsigned*)(lds + (bufoff) + ldsw + _i * 8192), 16, 0, 0); } while (0)
; #define PG8_LDA(dst, b, h) do { _Pragma("unroll") for (int m = 0; m < 4; ++m) _Pragma("unroll") for (int k = 0; k < 2; ++k) dst[m][k] = *(const PG8_LAS bf16x8*)(lds + PG8_SA(b, h) + aoff + m * 2048 + k * 1024); } while (0)
; #define PG8_LDB(dst, b, h) do { _Pragma("unroll") for (int n = 0; n < 2; ++n) _Pragma("unroll") for (int k = 0; k < 2; ++k) dst[n][k] = *(const PG8_LAS bf16x8*)(lds + PG8_SB(b, h) + boff + n * 2048 + k * 1024); } while (0)
; #define PG8_MMA(ai, bj, At, Bt) do { __builtin_amdgcn_s_setprio(1); _Pragma("unroll") for (int m = 0; m < 4; ++m) _Pragma("unroll") for (int n = 0; n < 2; ++n) _Pragma("unroll") for (int k = 0; k < 2; ++k) \
;         acc[ai][bj][m][n] = __builtin_amdgcn_mfma_f32_16x16x32_bf16(Bt[n][k], At[m][k], acc[ai][bj][m][n], 0, 0, 0); __builtin_amdgcn_s_setprio(0); } while (0)
; #define PG8_WAIT_V(n) asm volatile("s_waitcnt vmcnt(" #n ")" ::: "memory")
; #define PG8_WAIT_L(n) asm volatile("s_waitcnt lgkmcnt(" #n ")" ::: "memory")
; #define PG8_BAR __builtin_amdgcn_s_barrier()
; #define PG8_SCHED __builtin_amdgcn_sched_barrier(0)
; template <class Epi, class Sched, bool ALIGN_EPI = false, bool SP2 = false>
; __device__ __forceinline__ void gemm_phase(PG8_LAS unsigned char* lds, const Gemm g, const Sched& S, const Epi& E) {
;     ...
;             PG8_WAIT_V(8); PG8_WAIT_L(0); PG8_BAR; PG8_MMA(1, 0, At, B0); PG8_MMA(1, 1, At, B1); PG8_BAR; PG8_SCHED;
;             PG8_LDB(B0, 1, 0); PG8_LDB(B1, 1, 1); PG8_SCHED; PG8_LDA(At, 1, 0); PG8_STAGE(PG8_SA(0, 1), a2 + hstep, voffA);
;             PG8_WAIT_V(8); PG8_WAIT_L(0); PG8_BAR; PG8_MMA(0, 0, At, B0); PG8_MMA(0, 1, At, B1); PG8_BAR; PG8_SCHED;
	s_setprio 1
	s_waitcnt lgkmcnt(0)
	v_mfma_f32_16x16x32_bf16 v[16:19], v[156:159], v[218:221], v[16:19]
	v_mfma_f32_16x16x32_bf16 v[12:15], v[164:167], v[218:221], v[12:15]
	v_mfma_f32_16x16x32_bf16 v[64:67], v[160:163], v[198:201], v[64:67]
	v_mfma_f32_16x16x32_bf16 v[60:63], v[172:175], v[198:201], v[60:63]
	v_mfma_f32_16x16x32_bf16 v[48:51], v[160:163], v[206:209], v[48:51]
	v_mfma_f32_16x16x32_bf16 v[44:47], v[172:175], v[206:209], v[44:47]
	v_mfma_f32_16x16x32_bf16 v[32:35], v[160:163], v[214:217], v[32:35]
	v_mfma_f32_16x16x32_bf16 v[28:31], v[172:175], v[214:217], v[28:31]
	v_mfma_f32_16x16x32_bf16 v[16:19], v[160:163], v[222:225], v[16:19]
	v_mfma_f32_16x16x32_bf16 v[12:15], v[172:175], v[222:225], v[12:15]
	s_setprio 0
	s_setprio 1
	v_mfma_f32_16x16x32_bf16 v[56:59], v[176:179], v[192:195], v[56:59]
	v_mfma_f32_16x16x32_bf16 v[52:55], v[184:187], v[192:195], v[52:55]
	v_mfma_f32_16x16x32_bf16 v[40:43], v[176:179], v[202:205], v[40:43]
	v_mfma_f32_16x16x32_bf16 v[36:39], v[184:187], v[202:205], v[36:39]
	v_mfma_f32_16x16x32_bf16 v[24:27], v[176:179], v[210:213], v[24:27]
	v_mfma_f32_16x16x32_bf16 v[20:23], v[184:187], v[210:213], v[20:23]
	v_mfma_f32_16x16x32_bf16 v[8:11], v[176:179], v[218:221], v[8:11]
	v_mfma_f32_16x16x32_bf16 v[4:7], v[184:187], v[218:221], v[4:7]
	v_mfma_f32_16x16x32_bf16 v[56:59], v[180:183], v[198:201], v[56:59]
	v_mfma_f32_16x16x32_bf16 v[52:55], v[188:191], v[198:201], v[52:55]
	v_mfma_f32_16x16x32_bf16 v[40:43], v[180:183], v[206:209], v[40:43]
	v_mfma_f32_16x16x32_bf16 v[36:39], v[188:191], v[206:209], v[36:39]
	v_mfma_f32_16x16x32_bf16 v[24:27], v[180:183], v[214:217], v[24:27]
	v_mfma_f32_16x16x32_bf16 v[20:23], v[188:191], v[214:217], v[20:23]
	v_mfma_f32_16x16x32_bf16 v[8:11], v[180:183], v[222:225], v[8:11]
	v_mfma_f32_16x16x32_bf16 v[4:7], v[188:191], v[222:225], v[4:7]
	s_setprio 0
	s_barrier
	s_add_i32 s49, 0, 0x18000
	v_add_u32_e32 v155, s49, v153
	s_add_i32 s52, 0, 0x1c000
	ds_read_b128 v[156:159], v155
	ds_read_b128 v[160:163], v155 offset:1024
	ds_read_b128 v[164:167], v155 offset:2048
	ds_read_b128 v[172:175], v155 offset:3072
	v_add_u32_e32 v155, s52, v153
	ds_read_b128 v[176:179], v155
	ds_read_b128 v[180:183], v155 offset:1024
	ds_read_b128 v[184:187], v155 offset:2048
	ds_read_b128 v[188:191], v155 offset:3072
	s_add_u32 s16, s16, 0xb0000
	s_addc_u32 s17, s17, 0
	s_mov_b32 m0, s34
	v_lshl_add_u64 v[234:235], s[16:17], 0, v[132:133]
	ds_read_b128 v[192:195], v154 offset:32768
	ds_read_b128 v[198:201], v154 offset:33792
	ds_read_b128 v[202:205], v154 offset:34816
	ds_read_b128 v[206:209], v154 offset:35840
	ds_read_b128 v[210:213], v154 offset:36864
	ds_read_b128 v[214:217], v154 offset:37888
	ds_read_b128 v[218:221], v154 offset:38912
	ds_read_b128 v[222:225], v154 offset:39936
	global_load_lds_dwordx4 v[234:235], off
	v_lshl_add_u64 v[234:235], s[16:17], 0, v[136:137]
	s_mov_b32 m0, s35
	s_nop 0
	global_load_lds_dwordx4 v[234:235], off
	s_waitcnt vmcnt(8)
	s_waitcnt lgkmcnt(0)
	v_mfma_f32_16x16x32_bf16 v[112:115], v[156:159], v[192:195], v[112:115]
	v_mfma_f32_16x16x32_bf16 v[124:127], v[164:167], v[192:195], v[124:127]
	v_mfma_f32_16x16x32_bf16 v[96:99], v[156:159], v[202:205], v[96:99]
	v_mfma_f32_16x16x32_bf16 v[128:131], v[164:167], v[202:205], v[128:131]
	v_mfma_f32_16x16x32_bf16 v[100:103], v[156:159], v[210:213], v[100:103]
	v_mfma_f32_16x16x32_bf16 v[116:119], v[164:167], v[210:213], v[116:119]
	s_barrier
	s_setprio 1
	s_waitcnt lgkmcnt(0)
	v_mfma_f32_16x16x32_bf16 v[104:107], v[156:159], v[218:221], v[104:107]
	v_mfma_f32_16x16x32_bf16 v[120:123], v[164:167], v[218:221], v[120:123]
	v_mfma_f32_16x16x32_bf16 v[112:115], v[160:163], v[198:201], v[112:115]
	v_mfma_f32_16x16x32_bf16 v[124:127], v[172:175], v[198:201], v[124:127]
	v_mfma_f32_16x16x32_bf16 v[96:99], v[160:163], v[206:209], v[96:99]
	v_mfma_f32_16x16x32_bf16 v[128:131], v[172:175], v[206:209], v[128:131]
	v_mfma_f32_16x16x32_bf16 v[100:103], v[160:163], v[214:217], v[100:103]
	v_mfma_f32_16x16x32_bf16 v[116:119], v[172:175], v[214:217], v[116:119]
	v_mfma_f32_16x16x32_bf16 v[104:107], v[160:163], v[222:225], v[104:107]
	v_mfma_f32_16x16x32_bf16 v[120:123], v[172:175], v[222:225], v[120:123]
	s_setprio 0
	s_setprio 1
	v_mfma_f32_16x16x32_bf16 v[108:111], v[176:179], v[192:195], v[108:111]
	v_mfma_f32_16x16x32_bf16 v[92:95], v[184:187], v[192:195], v[92:95]
	v_mfma_f32_16x16x32_bf16 v[80:83], v[176:179], v[202:205], v[80:83]
	v_mfma_f32_16x16x32_bf16 v[68:71], v[184:187], v[202:205], v[68:71]
	v_mfma_f32_16x16x32_bf16 v[84:87], v[176:179], v[210:213], v[84:87]
	v_mfma_f32_16x16x32_bf16 v[72:75], v[184:187], v[210:213], v[72:75]
	v_mfma_f32_16x16x32_bf16 v[88:91], v[176:179], v[218:221], v[88:91]
	v_mfma_f32_16x16x32_bf16 v[76:79], v[184:187], v[218:221], v[76:79]
	v_mfma_f32_16x16x32_bf16 v[108:111], v[180:183], v[198:201], v[108:111]
	v_mfma_f32_16x16x32_bf16 v[92:95], v[188:191], v[198:201], v[92:95]
	v_mfma_f32_16x16x32_bf16 v[80:83], v[180:183], v[206:209], v[80:83]
	v_mfma_f32_16x16x32_bf16 v[68:71], v[188:191], v[206:209], v[68:71]
	v_mfma_f32_16x16x32_bf16 v[84:87], v[180:183], v[214:217], v[84:87]
	v_mfma_f32_16x16x32_bf16 v[72:75], v[188:191], v[214:217], v[72:75]
	v_mfma_f32_16x16x32_bf16 v[88:91], v[180:183], v[222:225], v[88:91]
	v_mfma_f32_16x16x32_bf16 v[76:79], v[188:191], v[222:225], v[76:79]
	s_setprio 0
	s_barrier
; #define PG8_STAGE(bufoff, gbase, voff) do { _Pragma("unroll") for (int _i = 0; _i < 2; ++_i) \
;         __builtin_amdgcn_global_load_lds((const unsigned*)((const char*)(gbase) + (voff)[_i]), (PG8_LAS unsigned*)(lds + (bufoff) + ldsw + _i * 8192), 16, 0, 0); } while (0)
; #define PG8_LDA(dst, b, h) do { _Pragma("unroll") for (int m = 0; m < 4; ++m) _Pragma("unroll") for (int k = 0; k < 2; ++k) dst[m][k] = *(const PG8_LAS bf16x8*)(lds + PG8_SA(b, h) + aoff + m * 2048 + k * 1024); } while (0)
; #define PG8_MMA(ai, bj, At, Bt) do { __builtin_amdgcn_s_setprio(1); _Pragma("unroll") for (int m = 0; m < 4; ++m) _Pragma("unroll") for (int n = 0; n < 2; ++n) _Pragma("unroll") for (int k = 0; k < 2; ++k) \
;         acc[ai][bj][m][n] = __builtin_amdgcn_mfma_f32_16x16x32_bf16(Bt[n][k], At[m][k], acc[ai][bj][m][n], 0, 0, 0); __builtin_amdgcn_s_setprio(0); } while (0)
; #define PG8_WAIT_V(n) asm volatile("s_waitcnt vmcnt(" #n ")" ::: "memory")
; #define PG8_WAIT_L(n) asm volatile("s_waitcnt lgkmcnt(" #n ")" ::: "memory")
; #define PG8_BAR __builtin_amdgcn_s_barrier()
; #define PG8_SCHED __builtin_amdgcn_sched_barrier(0)
; template <class Epi, class Sched, bool ALIGN_EPI = false, bool SP2 = false>
; __device__ __forceinline__ void gemm_phase(PG8_LAS unsigned char* lds, const Gemm g, const Sched& S, const Epi& E) {
;     ...
;             PG8_LDA(At, 1, 1); PG8_STAGE(PG8_SB(1, 0), b3, voffB); PG8_STAGE(PG8_SB(1, 1), b3 + hstep, voffB); PG8_STAGE(PG8_SA(1, 0), a3, voffA);
;             PG8_WAIT_V(8); PG8_WAIT_L(0); PG8_BAR; PG8_MMA(1, 0, At, B0); PG8_MMA(1, 1, At, B1); PG8_BAR; PG8_SCHED;
;     ...
;         if (!has_next) break;
; #pragma unroll
;         for (int a = 0; a < 2; ++a)
; #pragma unroll
;             for (int b = 0; b < 2; ++b)
; #pragma unroll
;                 for (int m = 0; m < 4; ++m)
; #pragma unroll
;                     for (int n = 0; n < 2; ++n) acc[a][b][m][n] = (f32x4){0.f, 0.f, 0.f, 0.f};
;         cur = nxt; cA = nA; cB = nB; ++ui;
	s_add_i32 s16, s49, s29
	v_lshl_add_u64 v[226:227], v[226:227], 0, s[14:15]
	s_mov_b32 m0, s16
	ds_read_b128 v[192:195], v154 offset:49152
	ds_read_b128 v[198:201], v154 offset:50176
	ds_read_b128 v[202:205], v154 offset:51200
	ds_read_b128 v[206:209], v154 offset:52224
	ds_read_b128 v[210:213], v154 offset:53248
	ds_read_b128 v[214:217], v154 offset:54272
	ds_read_b128 v[218:221], v154 offset:55296
	ds_read_b128 v[222:225], v154 offset:56320
	global_load_lds_dwordx4 v[226:227], off
	s_add_i32 m0, s16, 0x2000
	s_add_u32 s2, s2, 0xb0080
	v_lshl_add_u64 v[226:227], v[228:229], 0, s[14:15]
	s_addc_u32 s3, s3, 0
	s_add_i32 s16, s52, s29
	global_load_lds_dwordx4 v[226:227], off
	v_lshl_add_u64 v[226:227], s[2:3], 0, v[134:135]
	s_mov_b32 m0, s16
	s_nop 0
	global_load_lds_dwordx4 v[226:227], off
	v_lshl_add_u64 v[226:227], s[2:3], 0, v[138:139]
	s_add_i32 m0, s16, 0x2000
	s_nop 0
	global_load_lds_dwordx4 v[226:227], off
	v_lshl_add_u64 v[226:227], v[230:231], 0, s[14:15]
	s_mov_b32 m0, s38
	s_nop 0
	global_load_lds_dwordx4 v[226:227], off
	v_lshl_add_u64 v[226:227], v[232:233], 0, s[14:15]
	s_mov_b32 m0, s39
	s_nop 0
	global_load_lds_dwordx4 v[226:227], off
	s_waitcnt vmcnt(8)
	s_waitcnt lgkmcnt(0)
	v_mfma_f32_16x16x32_bf16 v[64:67], v[156:159], v[192:195], v[64:67]
	v_mfma_f32_16x16x32_bf16 v[60:63], v[164:167], v[192:195], v[60:63]
	v_mfma_f32_16x16x32_bf16 v[48:51], v[156:159], v[202:205], v[48:51]
	v_mfma_f32_16x16x32_bf16 v[44:47], v[164:167], v[202:205], v[44:47]
	v_mfma_f32_16x16x32_bf16 v[32:35], v[156:159], v[210:213], v[32:35]
	v_mfma_f32_16x16x32_bf16 v[28:31], v[164:167], v[210:213], v[28:31]
	s_barrier
	s_setprio 1
	s_waitcnt lgkmcnt(0)
	v_mfma_f32_16x16x32_bf16 v[16:19], v[156:159], v[218:221], v[16:19]
	v_mfma_f32_16x16x32_bf16 v[12:15], v[164:167], v[218:221], v[12:15]
	v_mfma_f32_16x16x32_bf16 v[64:67], v[160:163], v[198:201], v[64:67]
	v_mfma_f32_16x16x32_bf16 v[60:63], v[172:175], v[198:201], v[60:63]
	v_mfma_f32_16x16x32_bf16 v[48:51], v[160:163], v[206:209], v[48:51]
	v_mfma_f32_16x16x32_bf16 v[44:47], v[172:175], v[206:209], v[44:47]
	v_mfma_f32_16x16x32_bf16 v[32:35], v[160:163], v[214:217], v[32:35]
	v_mfma_f32_16x16x32_bf16 v[28:31], v[172:175], v[214:217], v[28:31]
	v_mfma_f32_16x16x32_bf16 v[16:19], v[160:163], v[222:225], v[16:19]
	v_mfma_f32_16x16x32_bf16 v[12:15], v[172:175], v[222:225], v[12:15]
	s_setprio 0
	s_setprio 1
	v_mfma_f32_16x16x32_bf16 v[56:59], v[176:179], v[192:195], v[56:59]
	v_mfma_f32_16x16x32_bf16 v[52:55], v[184:187], v[192:195], v[52:55]
	v_mfma_f32_16x16x32_bf16 v[40:43], v[176:179], v[202:205], v[40:43]
	v_mfma_f32_16x16x32_bf16 v[36:39], v[184:187], v[202:205], v[36:39]
	v_mfma_f32_16x16x32_bf16 v[24:27], v[176:179], v[210:213], v[24:27]
	v_mfma_f32_16x16x32_bf16 v[20:23], v[184:187], v[210:213], v[20:23]
	v_mfma_f32_16x16x32_bf16 v[8:11], v[176:179], v[218:221], v[8:11]
	v_mfma_f32_16x16x32_bf16 v[4:7], v[184:187], v[218:221], v[4:7]
	v_mfma_f32_16x16x32_bf16 v[56:59], v[180:183], v[198:201], v[56:59]
	v_mfma_f32_16x16x32_bf16 v[52:55], v[188:191], v[198:201], v[52:55]
	v_mfma_f32_16x16x32_bf16 v[40:43], v[180:183], v[206:209], v[40:43]
	v_mfma_f32_16x16x32_bf16 v[36:39], v[188:191], v[206:209], v[36:39]
	v_mfma_f32_16x16x32_bf16 v[24:27], v[180:183], v[214:217], v[24:27]
	v_mfma_f32_16x16x32_bf16 v[20:23], v[188:191], v[214:217], v[20:23]
	v_mfma_f32_16x16x32_bf16 v[8:11], v[180:183], v[222:225], v[8:11]
	v_mfma_f32_16x16x32_bf16 v[4:7], v[188:191], v[222:225], v[4:7]
	s_setprio 0
	s_barrier
	s_add_i32 s47, s47, 2
	s_add_u32 s22, s22, 0x100
	s_addc_u32 s23, s23, 0
	s_cmp_gt_u32 s47, 41
	s_cbranch_scc0 .LBB0_187
	s_add_u32 s2, s45, 0xffffff00
	s_addc_u32 s3, s46, -1
	s_and_b64 vcc, exec, s[6:7]
	s_cbranch_vccnz .LBB0_190
	v_mov_b32_e32 v4, 0
	s_mov_b32 s60, s42
	s_mov_b32 s25, s43
	s_mov_b64 s[12:13], s[20:21]
	s_mov_b32 s37, s44
	v_mov_b32_e32 v5, v4
	v_mov_b32_e32 v6, v4
	v_mov_b32_e32 v7, v4
	v_mov_b32_e32 v8, v4
	v_mov_b32_e32 v9, v4
	v_mov_b32_e32 v10, v4
	v_mov_b32_e32 v11, v4
	v_mov_b32_e32 v20, v4
	v_mov_b32_e32 v21, v4
	v_mov_b32_e32 v22, v4
	v_mov_b32_e32 v23, v4
	v_mov_b32_e32 v24, v4
	v_mov_b32_e32 v25, v4
	v_mov_b32_e32 v26, v4
	v_mov_b32_e32 v27, v4
	v_mov_b32_e32 v36, v4
	v_mov_b32_e32 v37, v4
	v_mov_b32_e32 v38, v4
	v_mov_b32_e32 v39, v4
	v_mov_b32_e32 v40, v4
	v_mov_b32_e32 v41, v4
	v_mov_b32_e32 v42, v4
	v_mov_b32_e32 v43, v4
	v_mov_b32_e32 v52, v4
	v_mov_b32_e32 v53, v4
	v_mov_b32_e32 v54, v4
	v_mov_b32_e32 v55, v4
	v_mov_b32_e32 v56, v4
	v_mov_b32_e32 v57, v4
	v_mov_b32_e32 v58, v4
	v_mov_b32_e32 v59, v4
	v_mov_b32_e32 v12, v4
	v_mov_b32_e32 v13, v4
	v_mov_b32_e32 v14, v4
	v_mov_b32_e32 v15, v4
	v_mov_b32_e32 v16, v4
	v_mov_b32_e32 v17, v4
	v_mov_b32_e32 v18, v4
	v_mov_b32_e32 v19, v4
	v_mov_b32_e32 v28, v4
	v_mov_b32_e32 v29, v4
	v_mov_b32_e32 v30, v4
	v_mov_b32_e32 v31, v4
	v_mov_b32_e32 v32, v4
	v_mov_b32_e32 v33, v4
	v_mov_b32_e32 v34, v4
	v_mov_b32_e32 v35, v4
	v_mov_b32_e32 v44, v4
	v_mov_b32_e32 v45, v4
	v_mov_b32_e32 v46, v4
	v_mov_b32_e32 v47, v4
	v_mov_b32_e32 v48, v4
	v_mov_b32_e32 v49, v4
	v_mov_b32_e32 v50, v4
	v_mov_b32_e32 v51, v4
	v_mov_b32_e32 v60, v4
	v_mov_b32_e32 v61, v4
	v_mov_b32_e32 v62, v4
	v_mov_b32_e32 v63, v4
	v_mov_b32_e32 v64, v4
	v_mov_b32_e32 v65, v4
	v_mov_b32_e32 v66, v4
	v_mov_b32_e32 v67, v4
	v_mov_b32_e32 v76, v4
	v_mov_b32_e32 v77, v4
	v_mov_b32_e32 v78, v4
	v_mov_b32_e32 v79, v4
	v_mov_b32_e32 v88, v4
	v_mov_b32_e32 v89, v4
	v_mov_b32_e32 v90, v4
	v_mov_b32_e32 v91, v4
	v_mov_b32_e32 v72, v4
	v_mov_b32_e32 v73, v4
	v_mov_b32_e32 v74, v4
	v_mov_b32_e32 v75, v4
	v_mov_b32_e32 v84, v4
	v_mov_b32_e32 v85, v4
	v_mov_b32_e32 v86, v4
	v_mov_b32_e32 v87, v4
	v_mov_b32_e32 v68, v4
	v_mov_b32_e32 v69, v4
	v_mov_b32_e32 v70, v4
	v_mov_b32_e32 v71, v4
	v_mov_b32_e32 v80, v4
	v_mov_b32_e32 v81, v4
	v_mov_b32_e32 v82, v4
	v_mov_b32_e32 v83, v4
	v_mov_b32_e32 v92, v4
	v_mov_b32_e32 v93, v4
	v_mov_b32_e32 v94, v4
	v_mov_b32_e32 v95, v4
	v_mov_b32_e32 v108, v4
	v_mov_b32_e32 v109, v4
	v_mov_b32_e32 v110, v4
	v_mov_b32_e32 v111, v4
	v_mov_b32_e32 v120, v4
	v_mov_b32_e32 v121, v4
	v_mov_b32_e32 v122, v4
	v_mov_b32_e32 v123, v4
	v_mov_b32_e32 v104, v4
	v_mov_b32_e32 v105, v4
	v_mov_b32_e32 v106, v4
	v_mov_b32_e32 v107, v4
	v_mov_b32_e32 v116, v4
	v_mov_b32_e32 v117, v4
	v_mov_b32_e32 v118, v4
	v_mov_b32_e32 v119, v4
	v_mov_b32_e32 v100, v4
	v_mov_b32_e32 v101, v4
	v_mov_b32_e32 v102, v4
	v_mov_b32_e32 v103, v4
	v_mov_b32_e32 v128, v4
	v_mov_b32_e32 v129, v4
	v_mov_b32_e32 v130, v4
	v_mov_b32_e32 v131, v4
	v_mov_b32_e32 v96, v4
	v_mov_b32_e32 v97, v4
	v_mov_b32_e32 v98, v4
	v_mov_b32_e32 v99, v4
	v_mov_b32_e32 v124, v4
	v_mov_b32_e32 v125, v4
	v_mov_b32_e32 v126, v4
	v_mov_b32_e32 v127, v4
	v_mov_b32_e32 v112, v4
	v_mov_b32_e32 v113, v4
	v_mov_b32_e32 v114, v4
	v_mov_b32_e32 v115, v4
	s_andn2_b64 vcc, exec, s[4:5]
	s_cbranch_vccnz .LBB0_191
	s_branch .LBB0_192

; #define PG8_STAGE(bufoff, gbase, voff) do { _Pragma("unroll") for (int _i = 0; _i < 2; ++_i) \
;         __builtin_amdgcn_global_load_lds((const unsigned*)((const char*)(gbase) + (voff)[_i]), (PG8_LAS unsigned*)(lds + (bufoff) + ldsw + _i * 8192), 16, 0, 0); } while (0)
; #define PG8_LDA(dst, b, h) do { _Pragma("unroll") for (int m = 0; m < 4; ++m) _Pragma("unroll") for (int k = 0; k < 2; ++k) dst[m][k] = *(const PG8_LAS bf16x8*)(lds + PG8_SA(b, h) + aoff + m * 2048 + k * 1024); } while (0)
; #define PG8_LDB(dst, b, h) do { _Pragma("unroll") for (int n = 0; n < 2; ++n) _Pragma("unroll") for (int k = 0; k < 2; ++k) dst[n][k] = *(const PG8_LAS bf16x8*)(lds + PG8_SB(b, h) + boff + n * 2048 + k * 1024); } while (0)
; #define PG8_MMA(ai, bj, At, Bt) do { __builtin_amdgcn_s_setprio(1); _Pragma("unroll") for (int m = 0; m < 4; ++m) _Pragma("unroll") for (int n = 0; n < 2; ++n) _Pragma("unroll") for (int k = 0; k < 2; ++k) \
;         acc[ai][bj][m][n] = __builtin_amdgcn_mfma_f32_16x16x32_bf16(Bt[n][k], At[m][k], acc[ai][bj][m][n], 0, 0, 0); __builtin_amdgcn_s_setprio(0); } while (0)
; #define PG8_WAIT_V(n) asm volatile("s_waitcnt vmcnt(" #n ")" ::: "memory")
; #define PG8_WAIT_L(n) asm volatile("s_waitcnt lgkmcnt(" #n ")" ::: "memory")
; template <class Epi, class Sched, bool ALIGN_EPI = false, bool SP2 = false>
; __device__ __forceinline__ void gemm_phase(PG8_LAS unsigned char* lds, const Gemm g, const Sched& S, const Epi& E) {
;     ...
;             const bool last = (t == nt - 2);
;             const char* a1 = cA + (size_t)(t + 1) * kstep;
;             const char* a2 = last ? nA : cA + (size_t)(t + 2) * kstep; const char* b2 = last ? nB : cB + (size_t)(t + 2) * kstep;
;             const char* a3 = a2 + kstep; const char* b3 = b2 + kstep;
;             if (last && has_next) S.a_ready(nxt);
;             if constexpr (SP2) {
;             PG8_LDB(B0, 0, 0); PG8_LDB(B1, 0, 1); PG8_SCHED; PG8_LDA(At, 0, 0); PG8_STAGE(PG8_SA(1, 1), a1 + hstep, voffA);
;             PG8_WAIT_V(8); PG8_WAIT_L(0); PG8_BAR; PG8_MMA(0, 0, At, B0); PG8_MMA(0, 1, At, B1); PG8_BAR; PG8_SCHED;
;             PG8_LDA(At, 0, 1); PG8_STAGE(PG8_SB(0, 0), b2, voffB); PG8_STAGE(PG8_SB(0, 1), b2 + hstep, voffB); PG8_STAGE(PG8_SA(0, 0), a2, voffA);
;             PG8_WAIT_V(8); PG8_WAIT_L(0); PG8_BAR; PG8_MMA(1, 0, At, B0); PG8_MMA(1, 1, At, B1); PG8_BAR; PG8_SCHED;
.LBB0_334:
	ds_read_b128 v[148:151], v164
	ds_read_b128 v[152:155], v164 offset:1024
	ds_read_b128 v[156:159], v164 offset:2048
	ds_read_b128 v[172:175], v164 offset:3072
	ds_read_b128 v[176:179], v165
	ds_read_b128 v[180:183], v165 offset:1024
	ds_read_b128 v[184:187], v165 offset:2048
	ds_read_b128 v[188:191], v165 offset:3072
	s_add_u32 s2, s10, 0xfffc0080
	s_addc_u32 s3, s11, -1
	s_cmp_eq_u32 s37, 12
	s_cselect_b32 s13, s7, s3
	s_cselect_b32 s12, s9, s2
	s_cselect_b32 s3, s14, s36
	s_cselect_b32 s2, s15, s29
	v_lshl_add_u64 v[160:161], s[10:11], 0, v[140:141]
	s_add_i32 m0, s17, 0xc000
	ds_read_b128 v[192:195], v166
	ds_read_b128 v[198:201], v166 offset:1024
	ds_read_b128 v[202:205], v166 offset:2048
	ds_read_b128 v[206:209], v166 offset:3072
	ds_read_b128 v[210:213], v166 offset:4096
	ds_read_b128 v[214:217], v166 offset:5120
	ds_read_b128 v[218:221], v166 offset:6144
	ds_read_b128 v[222:225], v166 offset:7168
	global_load_lds_dwordx4 v[160:161], off
	v_lshl_add_u64 v[160:161], s[10:11], 0, v[142:143]
	s_add_i32 m0, s17, 0xe000
	s_nop 0
	global_load_lds_dwordx4 v[160:161], off
	s_waitcnt vmcnt(8)
	s_waitcnt lgkmcnt(0)
	v_mfma_f32_16x16x32_bf16 v[126:129], v[148:151], v[192:195], v[126:129]
	v_mfma_f32_16x16x32_bf16 v[122:125], v[156:159], v[192:195], v[122:125]
	v_mfma_f32_16x16x32_bf16 v[110:113], v[148:151], v[202:205], v[110:113]
	v_mfma_f32_16x16x32_bf16 v[106:109], v[156:159], v[202:205], v[106:109]
	v_mfma_f32_16x16x32_bf16 v[94:97], v[148:151], v[210:213], v[94:97]
	v_mfma_f32_16x16x32_bf16 v[90:93], v[156:159], v[210:213], v[90:93]
	s_barrier
	s_setprio 1
	s_waitcnt lgkmcnt(0)
	v_mfma_f32_16x16x32_bf16 v[78:81], v[148:151], v[218:221], v[78:81]
	v_mfma_f32_16x16x32_bf16 v[74:77], v[156:159], v[218:221], v[74:77]
	v_mfma_f32_16x16x32_bf16 v[126:129], v[152:155], v[198:201], v[126:129]
	v_mfma_f32_16x16x32_bf16 v[122:125], v[172:175], v[198:201], v[122:125]
	v_mfma_f32_16x16x32_bf16 v[110:113], v[152:155], v[206:209], v[110:113]
	v_mfma_f32_16x16x32_bf16 v[106:109], v[172:175], v[206:209], v[106:109]
	v_mfma_f32_16x16x32_bf16 v[94:97], v[152:155], v[214:217], v[94:97]
	v_mfma_f32_16x16x32_bf16 v[90:93], v[172:175], v[214:217], v[90:93]
	v_mfma_f32_16x16x32_bf16 v[78:81], v[152:155], v[222:225], v[78:81]
	v_mfma_f32_16x16x32_bf16 v[74:77], v[172:175], v[222:225], v[74:77]
	s_setprio 0
	s_setprio 1
	v_mfma_f32_16x16x32_bf16 v[118:121], v[176:179], v[192:195], v[118:121]
	v_mfma_f32_16x16x32_bf16 v[114:117], v[184:187], v[192:195], v[114:117]
	v_mfma_f32_16x16x32_bf16 v[102:105], v[176:179], v[202:205], v[102:105]
	v_mfma_f32_16x16x32_bf16 v[98:101], v[184:187], v[202:205], v[98:101]
	v_mfma_f32_16x16x32_bf16 v[86:89], v[176:179], v[210:213], v[86:89]
	v_mfma_f32_16x16x32_bf16 v[82:85], v[184:187], v[210:213], v[82:85]
	v_mfma_f32_16x16x32_bf16 v[70:73], v[176:179], v[218:221], v[70:73]
	v_mfma_f32_16x16x32_bf16 v[66:69], v[184:187], v[218:221], v[66:69]
	v_mfma_f32_16x16x32_bf16 v[118:121], v[180:183], v[198:201], v[118:121]
	v_mfma_f32_16x16x32_bf16 v[114:117], v[188:191], v[198:201], v[114:117]
	v_mfma_f32_16x16x32_bf16 v[102:105], v[180:183], v[206:209], v[102:105]
	v_mfma_f32_16x16x32_bf16 v[98:101], v[188:191], v[206:209], v[98:101]
	v_mfma_f32_16x16x32_bf16 v[86:89], v[180:183], v[214:217], v[86:89]
	v_mfma_f32_16x16x32_bf16 v[82:85], v[188:191], v[214:217], v[82:85]
	v_mfma_f32_16x16x32_bf16 v[70:73], v[180:183], v[222:225], v[70:73]
	v_mfma_f32_16x16x32_bf16 v[66:69], v[188:191], v[222:225], v[66:69]
	s_setprio 0
	s_barrier
	s_add_i32 s38, s44, s16
	v_lshl_add_u64 v[160:161], s[2:3], 0, v[132:133]
	s_mov_b32 m0, s38
	ds_read_b128 v[192:195], v166 offset:16384
	ds_read_b128 v[198:201], v166 offset:17408
	ds_read_b128 v[202:205], v166 offset:18432
	ds_read_b128 v[206:209], v166 offset:19456
	ds_read_b128 v[210:213], v166 offset:20480
	ds_read_b128 v[214:217], v166 offset:21504
	ds_read_b128 v[218:221], v166 offset:22528
	ds_read_b128 v[222:225], v166 offset:23552
	global_load_lds_dwordx4 v[160:161], off
	s_add_i32 m0, s38, 0x2000
	s_add_u32 s38, s2, 0x40000
	v_lshl_add_u64 v[226:227], s[2:3], 0, v[136:137]
	s_addc_u32 s39, s3, 0
	s_add_i32 s40, s45, s16
	global_load_lds_dwordx4 v[226:227], off
	v_lshl_add_u64 v[228:229], s[38:39], 0, v[132:133]
	s_mov_b32 m0, s40
	v_lshl_add_u64 v[230:231], s[12:13], 0, v[134:135]
	global_load_lds_dwordx4 v[228:229], off
	v_lshl_add_u64 v[228:229], s[38:39], 0, v[136:137]
	s_add_i32 m0, s40, 0x2000
	s_nop 0
	global_load_lds_dwordx4 v[228:229], off
	v_lshl_add_u64 v[228:229], s[12:13], 0, v[130:131]
	s_mov_b32 m0, s17
	s_nop 0
	global_load_lds_dwordx4 v[228:229], off
	s_mov_b32 m0, s24
	s_nop 0
	global_load_lds_dwordx4 v[230:231], off
	s_waitcnt vmcnt(8)
	s_waitcnt lgkmcnt(0)
	v_mfma_f32_16x16x32_bf16 v[62:65], v[148:151], v[192:195], v[62:65]
	v_mfma_f32_16x16x32_bf16 v[58:61], v[156:159], v[192:195], v[58:61]
	v_mfma_f32_16x16x32_bf16 v[46:49], v[148:151], v[202:205], v[46:49]
	v_mfma_f32_16x16x32_bf16 v[42:45], v[156:159], v[202:205], v[42:45]
	v_mfma_f32_16x16x32_bf16 v[30:33], v[148:151], v[210:213], v[30:33]
	v_mfma_f32_16x16x32_bf16 v[26:29], v[156:159], v[210:213], v[26:29]
	s_barrier
; #define PG8_STAGE(bufoff, gbase, voff) do { _Pragma("unroll") for (int _i = 0; _i < 2; ++_i) \
;         __builtin_amdgcn_global_load_lds((const unsigned*)((const char*)(gbase) + (voff)[_i]), (PG8_LAS unsigned*)(lds + (bufoff) + ldsw + _i * 8192), 16, 0, 0); } while (0)
; #define PG8_LDA(dst, b, h) do { _Pragma("unroll") for (int m = 0; m < 4; ++m) _Pragma("unroll") for (int k = 0; k < 2; ++k) dst[m][k] = *(const PG8_LAS bf16x8*)(lds + PG8_SA(b, h) + aoff + m * 2048 + k * 1024); } while (0)
; #define PG8_LDB(dst, b, h) do { _Pragma("unroll") for (int n = 0; n < 2; ++n) _Pragma("unroll") for (int k = 0; k < 2; ++k) dst[n][k] = *(const PG8_LAS bf16x8*)(lds + PG8_SB(b, h) + boff + n * 2048 + k * 1024); } while (0)
; #define PG8_MMA(ai, bj, At, Bt) do { __builtin_amdgcn_s_setprio(1); _Pragma("unroll") for (int m = 0; m < 4; ++m) _Pragma("unroll") for (int n = 0; n < 2; ++n) _Pragma("unroll") for (int k = 0; k < 2; ++k) \
;         acc[ai][bj][m][n] = __builtin_amdgcn_mfma_f32_16x16x32_bf16(Bt[n][k], At[m][k], acc[ai][bj][m][n], 0, 0, 0); __builtin_amdgcn_s_setprio(0); } while (0)
; #define PG8_WAIT_V(n) asm volatile("s_waitcnt vmcnt(" #n ")" ::: "memory")
; #define PG8_WAIT_L(n) asm volatile("s_waitcnt lgkmcnt(" #n ")" ::: "memory")
; #define PG8_BAR __builtin_amdgcn_s_barrier()
; #define PG8_SCHED __builtin_amdgcn_sched_barrier(0)
; template <class Epi, class Sched, bool ALIGN_EPI = false, bool SP2 = false>
; __device__ __forceinline__ void gemm_phase(PG8_LAS unsigned char* lds, const Gemm g, const Sched& S, const Epi& E) {
;     ...
;             PG8_WAIT_V(8); PG8_WAIT_L(0); PG8_BAR; PG8_MMA(1, 0, At, B0); PG8_MMA(1, 1, At, B1); PG8_BAR; PG8_SCHED;
;             PG8_LDB(B0, 1, 0); PG8_LDB(B1, 1, 1); PG8_SCHED; PG8_LDA(At, 1, 0); PG8_STAGE(PG8_SA(0, 1), a2 + hstep, voffA);
;             PG8_WAIT_V(8); PG8_WAIT_L(0); PG8_BAR; PG8_MMA(0, 0, At, B0); PG8_MMA(0, 1, At, B1); PG8_BAR; PG8_SCHED;
	s_setprio 1
	s_waitcnt lgkmcnt(0)
	v_mfma_f32_16x16x32_bf16 v[14:17], v[148:151], v[218:221], v[14:17]
	v_mfma_f32_16x16x32_bf16 v[10:13], v[156:159], v[218:221], v[10:13]
	v_mfma_f32_16x16x32_bf16 v[62:65], v[152:155], v[198:201], v[62:65]
	v_mfma_f32_16x16x32_bf16 v[58:61], v[172:175], v[198:201], v[58:61]
	v_mfma_f32_16x16x32_bf16 v[46:49], v[152:155], v[206:209], v[46:49]
	v_mfma_f32_16x16x32_bf16 v[42:45], v[172:175], v[206:209], v[42:45]
	v_mfma_f32_16x16x32_bf16 v[30:33], v[152:155], v[214:217], v[30:33]
	v_mfma_f32_16x16x32_bf16 v[26:29], v[172:175], v[214:217], v[26:29]
	v_mfma_f32_16x16x32_bf16 v[14:17], v[152:155], v[222:225], v[14:17]
	v_mfma_f32_16x16x32_bf16 v[10:13], v[172:175], v[222:225], v[10:13]
	s_setprio 0
	s_setprio 1
	v_mfma_f32_16x16x32_bf16 v[54:57], v[176:179], v[192:195], v[54:57]
	v_mfma_f32_16x16x32_bf16 v[50:53], v[184:187], v[192:195], v[50:53]
	v_mfma_f32_16x16x32_bf16 v[38:41], v[176:179], v[202:205], v[38:41]
	v_mfma_f32_16x16x32_bf16 v[34:37], v[184:187], v[202:205], v[34:37]
	v_mfma_f32_16x16x32_bf16 v[22:25], v[176:179], v[210:213], v[22:25]
	v_mfma_f32_16x16x32_bf16 v[18:21], v[184:187], v[210:213], v[18:21]
	v_mfma_f32_16x16x32_bf16 v[6:9], v[176:179], v[218:221], v[6:9]
	v_mfma_f32_16x16x32_bf16 v[2:5], v[184:187], v[218:221], v[2:5]
	v_mfma_f32_16x16x32_bf16 v[54:57], v[180:183], v[198:201], v[54:57]
	v_mfma_f32_16x16x32_bf16 v[50:53], v[188:191], v[198:201], v[50:53]
	v_mfma_f32_16x16x32_bf16 v[38:41], v[180:183], v[206:209], v[38:41]
	v_mfma_f32_16x16x32_bf16 v[34:37], v[188:191], v[206:209], v[34:37]
	v_mfma_f32_16x16x32_bf16 v[22:25], v[180:183], v[214:217], v[22:25]
	v_mfma_f32_16x16x32_bf16 v[18:21], v[188:191], v[214:217], v[18:21]
	v_mfma_f32_16x16x32_bf16 v[6:9], v[180:183], v[222:225], v[6:9]
	v_mfma_f32_16x16x32_bf16 v[2:5], v[188:191], v[222:225], v[2:5]
	s_setprio 0
	s_barrier
	s_add_i32 s38, 0, 0x18000
	v_add_u32_e32 v138, s38, v162
	s_add_i32 s39, 0, 0x1c000
	ds_read_b128 v[148:151], v138
	ds_read_b128 v[152:155], v138 offset:1024
	ds_read_b128 v[156:159], v138 offset:2048
	ds_read_b128 v[172:175], v138 offset:3072
	v_add_u32_e32 v138, s39, v162
	ds_read_b128 v[176:179], v138
	ds_read_b128 v[180:183], v138 offset:1024
	ds_read_b128 v[184:187], v138 offset:2048
	ds_read_b128 v[188:191], v138 offset:3072
	s_add_u32 s12, s12, 0x40000
	s_addc_u32 s13, s13, 0
	s_mov_b32 m0, s25
	v_lshl_add_u64 v[232:233], s[12:13], 0, v[130:131]
	ds_read_b128 v[192:195], v166 offset:32768
	ds_read_b128 v[198:201], v166 offset:33792
	ds_read_b128 v[202:205], v166 offset:34816
	ds_read_b128 v[206:209], v166 offset:35840
	ds_read_b128 v[210:213], v166 offset:36864
	ds_read_b128 v[214:217], v166 offset:37888
	ds_read_b128 v[218:221], v166 offset:38912
	ds_read_b128 v[222:225], v166 offset:39936
	global_load_lds_dwordx4 v[232:233], off
	v_lshl_add_u64 v[232:233], s[12:13], 0, v[134:135]
	s_mov_b32 m0, s26
	s_nop 0
	global_load_lds_dwordx4 v[232:233], off
	s_waitcnt vmcnt(8)
	s_waitcnt lgkmcnt(0)
	v_mfma_f32_16x16x32_bf16 v[126:129], v[148:151], v[192:195], v[126:129]
	v_mfma_f32_16x16x32_bf16 v[122:125], v[156:159], v[192:195], v[122:125]
	v_mfma_f32_16x16x32_bf16 v[110:113], v[148:151], v[202:205], v[110:113]
	v_mfma_f32_16x16x32_bf16 v[106:109], v[156:159], v[202:205], v[106:109]
	v_mfma_f32_16x16x32_bf16 v[94:97], v[148:151], v[210:213], v[94:97]
	v_mfma_f32_16x16x32_bf16 v[90:93], v[156:159], v[210:213], v[90:93]
	s_barrier
	s_setprio 1
	s_waitcnt lgkmcnt(0)
	v_mfma_f32_16x16x32_bf16 v[78:81], v[148:151], v[218:221], v[78:81]
	v_mfma_f32_16x16x32_bf16 v[74:77], v[156:159], v[218:221], v[74:77]
	v_mfma_f32_16x16x32_bf16 v[126:129], v[152:155], v[198:201], v[126:129]
	v_mfma_f32_16x16x32_bf16 v[122:125], v[172:175], v[198:201], v[122:125]
	v_mfma_f32_16x16x32_bf16 v[110:113], v[152:155], v[206:209], v[110:113]
	v_mfma_f32_16x16x32_bf16 v[106:109], v[172:175], v[206:209], v[106:109]
	v_mfma_f32_16x16x32_bf16 v[94:97], v[152:155], v[214:217], v[94:97]
	v_mfma_f32_16x16x32_bf16 v[90:93], v[172:175], v[214:217], v[90:93]
	v_mfma_f32_16x16x32_bf16 v[78:81], v[152:155], v[222:225], v[78:81]
	v_mfma_f32_16x16x32_bf16 v[74:77], v[172:175], v[222:225], v[74:77]
	s_setprio 0
	s_setprio 1
	v_mfma_f32_16x16x32_bf16 v[118:121], v[176:179], v[192:195], v[118:121]
	v_mfma_f32_16x16x32_bf16 v[114:117], v[184:187], v[192:195], v[114:117]
	v_mfma_f32_16x16x32_bf16 v[102:105], v[176:179], v[202:205], v[102:105]
	v_mfma_f32_16x16x32_bf16 v[98:101], v[184:187], v[202:205], v[98:101]
	v_mfma_f32_16x16x32_bf16 v[86:89], v[176:179], v[210:213], v[86:89]
	v_mfma_f32_16x16x32_bf16 v[82:85], v[184:187], v[210:213], v[82:85]
	v_mfma_f32_16x16x32_bf16 v[70:73], v[176:179], v[218:221], v[70:73]
	v_mfma_f32_16x16x32_bf16 v[66:69], v[184:187], v[218:221], v[66:69]
	v_mfma_f32_16x16x32_bf16 v[118:121], v[180:183], v[198:201], v[118:121]
	v_mfma_f32_16x16x32_bf16 v[114:117], v[188:191], v[198:201], v[114:117]
	v_mfma_f32_16x16x32_bf16 v[102:105], v[180:183], v[206:209], v[102:105]
	v_mfma_f32_16x16x32_bf16 v[98:101], v[188:191], v[206:209], v[98:101]
	v_mfma_f32_16x16x32_bf16 v[86:89], v[180:183], v[214:217], v[86:89]
	v_mfma_f32_16x16x32_bf16 v[82:85], v[188:191], v[214:217], v[82:85]
	v_mfma_f32_16x16x32_bf16 v[70:73], v[180:183], v[222:225], v[70:73]
	v_mfma_f32_16x16x32_bf16 v[66:69], v[188:191], v[222:225], v[66:69]
	s_setprio 0
	s_barrier
; #define PG8_STAGE(bufoff, gbase, voff) do { _Pragma("unroll") for (int _i = 0; _i < 2; ++_i) \
;         __builtin_amdgcn_global_load_lds((const unsigned*)((const char*)(gbase) + (voff)[_i]), (PG8_LAS unsigned*)(lds + (bufoff) + ldsw + _i * 8192), 16, 0, 0); } while (0)
; #define PG8_LDA(dst, b, h) do { _Pragma("unroll") for (int m = 0; m < 4; ++m) _Pragma("unroll") for (int k = 0; k < 2; ++k) dst[m][k] = *(const PG8_LAS bf16x8*)(lds + PG8_SA(b, h) + aoff + m * 2048 + k * 1024); } while (0)
; #define PG8_MMA(ai, bj, At, Bt) do { __builtin_amdgcn_s_setprio(1); _Pragma("unroll") for (int m = 0; m < 4; ++m) _Pragma("unroll") for (int n = 0; n < 2; ++n) _Pragma("unroll") for (int k = 0; k < 2; ++k) \
;         acc[ai][bj][m][n] = __builtin_amdgcn_mfma_f32_16x16x32_bf16(Bt[n][k], At[m][k], acc[ai][bj][m][n], 0, 0, 0); __builtin_amdgcn_s_setprio(0); } while (0)
; #define PG8_WAIT_V(n) asm volatile("s_waitcnt vmcnt(" #n ")" ::: "memory")
; #define PG8_WAIT_L(n) asm volatile("s_waitcnt lgkmcnt(" #n ")" ::: "memory")
; #define PG8_BAR __builtin_amdgcn_s_barrier()
; #define PG8_SCHED __builtin_amdgcn_sched_barrier(0)
; template <class Epi, class Sched, bool ALIGN_EPI = false, bool SP2 = false>
; __device__ __forceinline__ void gemm_phase(PG8_LAS unsigned char* lds, const Gemm g, const Sched& S, const Epi& E) {
;     ...
;             PG8_LDA(At, 1, 1); PG8_STAGE(PG8_SB(1, 0), b3, voffB); PG8_STAGE(PG8_SB(1, 1), b3 + hstep, voffB); PG8_STAGE(PG8_SA(1, 0), a3, voffA);
;             PG8_WAIT_V(8); PG8_WAIT_L(0); PG8_BAR; PG8_MMA(1, 0, At, B0); PG8_MMA(1, 1, At, B1); PG8_BAR; PG8_SCHED;
;     ...
;         if constexpr (ALIGN_EPI) { if (wr == 0) PG8_BAR; }
	s_add_i32 s12, s38, s16
	v_lshl_add_u64 v[160:161], v[160:161], 0, s[20:21]
	s_mov_b32 m0, s12
	ds_read_b128 v[192:195], v166 offset:49152
	ds_read_b128 v[198:201], v166 offset:50176
	ds_read_b128 v[202:205], v166 offset:51200
	ds_read_b128 v[206:209], v166 offset:52224
	ds_read_b128 v[210:213], v166 offset:53248
	ds_read_b128 v[214:217], v166 offset:54272
	ds_read_b128 v[218:221], v166 offset:55296
	ds_read_b128 v[222:225], v166 offset:56320
	global_load_lds_dwordx4 v[160:161], off
	s_add_i32 m0, s12, 0x2000
	s_add_u32 s2, s2, 0x40080
	v_lshl_add_u64 v[160:161], v[226:227], 0, s[20:21]
	s_addc_u32 s3, s3, 0
	s_add_i32 s12, s39, s16
	global_load_lds_dwordx4 v[160:161], off
	v_lshl_add_u64 v[160:161], s[2:3], 0, v[132:133]
	s_mov_b32 m0, s12
	s_nop 0
	global_load_lds_dwordx4 v[160:161], off
	v_lshl_add_u64 v[160:161], s[2:3], 0, v[136:137]
	s_add_i32 m0, s12, 0x2000
	s_nop 0
	global_load_lds_dwordx4 v[160:161], off
	v_lshl_add_u64 v[160:161], v[228:229], 0, s[20:21]
	s_mov_b32 m0, s34
	s_nop 0
	global_load_lds_dwordx4 v[160:161], off
	v_lshl_add_u64 v[160:161], v[230:231], 0, s[20:21]
	s_mov_b32 m0, s35
	s_nop 0
	global_load_lds_dwordx4 v[160:161], off
	s_waitcnt vmcnt(8)
	s_waitcnt lgkmcnt(0)
	v_mfma_f32_16x16x32_bf16 v[62:65], v[148:151], v[192:195], v[62:65]
	v_mfma_f32_16x16x32_bf16 v[58:61], v[156:159], v[192:195], v[58:61]
	v_mfma_f32_16x16x32_bf16 v[46:49], v[148:151], v[202:205], v[46:49]
	v_mfma_f32_16x16x32_bf16 v[42:45], v[156:159], v[202:205], v[42:45]
	v_mfma_f32_16x16x32_bf16 v[30:33], v[148:151], v[210:213], v[30:33]
	v_mfma_f32_16x16x32_bf16 v[26:29], v[156:159], v[210:213], v[26:29]
	s_barrier
	s_setprio 1
	s_waitcnt lgkmcnt(0)
	v_mfma_f32_16x16x32_bf16 v[14:17], v[148:151], v[218:221], v[14:17]
	v_mfma_f32_16x16x32_bf16 v[10:13], v[156:159], v[218:221], v[10:13]
	v_mfma_f32_16x16x32_bf16 v[62:65], v[152:155], v[198:201], v[62:65]
	v_mfma_f32_16x16x32_bf16 v[58:61], v[172:175], v[198:201], v[58:61]
	v_mfma_f32_16x16x32_bf16 v[46:49], v[152:155], v[206:209], v[46:49]
	v_mfma_f32_16x16x32_bf16 v[42:45], v[172:175], v[206:209], v[42:45]
	v_mfma_f32_16x16x32_bf16 v[30:33], v[152:155], v[214:217], v[30:33]
	v_mfma_f32_16x16x32_bf16 v[26:29], v[172:175], v[214:217], v[26:29]
	v_mfma_f32_16x16x32_bf16 v[14:17], v[152:155], v[222:225], v[14:17]
	v_mfma_f32_16x16x32_bf16 v[10:13], v[172:175], v[222:225], v[10:13]
	s_setprio 0
	s_setprio 1
	v_mfma_f32_16x16x32_bf16 v[54:57], v[176:179], v[192:195], v[54:57]
	v_mfma_f32_16x16x32_bf16 v[50:53], v[184:187], v[192:195], v[50:53]
	v_mfma_f32_16x16x32_bf16 v[38:41], v[176:179], v[202:205], v[38:41]
	v_mfma_f32_16x16x32_bf16 v[34:37], v[184:187], v[202:205], v[34:37]
	v_mfma_f32_16x16x32_bf16 v[22:25], v[176:179], v[210:213], v[22:25]
	v_mfma_f32_16x16x32_bf16 v[18:21], v[184:187], v[210:213], v[18:21]
	v_mfma_f32_16x16x32_bf16 v[6:9], v[176:179], v[218:221], v[6:9]
	v_mfma_f32_16x16x32_bf16 v[2:5], v[184:187], v[218:221], v[2:5]
	v_mfma_f32_16x16x32_bf16 v[54:57], v[180:183], v[198:201], v[54:57]
	v_mfma_f32_16x16x32_bf16 v[50:53], v[188:191], v[198:201], v[50:53]
	v_mfma_f32_16x16x32_bf16 v[38:41], v[180:183], v[206:209], v[38:41]
	v_mfma_f32_16x16x32_bf16 v[34:37], v[188:191], v[206:209], v[34:37]
	v_mfma_f32_16x16x32_bf16 v[22:25], v[180:183], v[214:217], v[22:25]
	v_mfma_f32_16x16x32_bf16 v[18:21], v[188:191], v[214:217], v[18:21]
	v_mfma_f32_16x16x32_bf16 v[6:9], v[180:183], v[222:225], v[6:9]
	v_mfma_f32_16x16x32_bf16 v[2:5], v[188:191], v[222:225], v[2:5]
	s_setprio 0
	s_barrier
	s_add_i32 s37, s37, 2
	s_add_u32 s10, s10, 0x100
	s_addc_u32 s11, s11, 0
	s_add_u32 s29, s29, 0x100
	s_addc_u32 s36, s36, 0
	s_cmp_gt_u32 s37, 13
	s_cbranch_scc0 .LBB0_334
	s_and_b64 vcc, exec, s[22:23]
	s_cbranch_vccz .LBB0_337
	s_barrier

; #define PG8_STAGE(bufoff, gbase, voff) do { _Pragma("unroll") for (int _i = 0; _i < 2; ++_i) \
;         __builtin_amdgcn_global_load_lds((const unsigned*)((const char*)(gbase) + (voff)[_i]), (PG8_LAS unsigned*)(lds + (bufoff) + ldsw + _i * 8192), 16, 0, 0); } while (0)
; #define PG8_LDA(dst, b, h) do { _Pragma("unroll") for (int m = 0; m < 4; ++m) _Pragma("unroll") for (int k = 0; k < 2; ++k) dst[m][k] = *(const PG8_LAS bf16x8*)(lds + PG8_SA(b, h) + aoff + m * 2048 + k * 1024); } while (0)
; #define PG8_LDB(dst, b, h) do { _Pragma("unroll") for (int n = 0; n < 2; ++n) _Pragma("unroll") for (int k = 0; k < 2; ++k) dst[n][k] = *(const PG8_LAS bf16x8*)(lds + PG8_SB(b, h) + boff + n * 2048 + k * 1024); } while (0)
; #define PG8_MMA(ai, bj, At, Bt) do { __builtin_amdgcn_s_setprio(1); _Pragma("unroll") for (int m = 0; m < 4; ++m) _Pragma("unroll") for (int n = 0; n < 2; ++n) _Pragma("unroll") for (int k = 0; k < 2; ++k) \
;         acc[ai][bj][m][n] = __builtin_amdgcn_mfma_f32_16x16x32_bf16(Bt[n][k], At[m][k], acc[ai][bj][m][n], 0, 0, 0); __builtin_amdgcn_s_setprio(0); } while (0)
; #define PG8_WAIT_V(n) asm volatile("s_waitcnt vmcnt(" #n ")" ::: "memory")
; #define PG8_WAIT_L(n) asm volatile("s_waitcnt lgkmcnt(" #n ")" ::: "memory")
; template <class Epi, class Sched, bool ALIGN_EPI = false, bool SP2 = false>
; __device__ __forceinline__ void gemm_phase(PG8_LAS unsigned char* lds, const Gemm g, const Sched& S, const Epi& E) {
;     ...
;             const bool last = (t == nt - 2);
;             const char* a1 = cA + (size_t)(t + 1) * kstep;
;             const char* a2 = last ? nA : cA + (size_t)(t + 2) * kstep; const char* b2 = last ? nB : cB + (size_t)(t + 2) * kstep;
;             const char* a3 = a2 + kstep; const char* b3 = b2 + kstep;
;             if (last && has_next) S.a_ready(nxt);
;             if constexpr (SP2) {
;             PG8_LDB(B0, 0, 0); PG8_LDB(B1, 0, 1); PG8_SCHED; PG8_LDA(At, 0, 0); PG8_STAGE(PG8_SA(1, 1), a1 + hstep, voffA);
;             PG8_WAIT_V(8); PG8_WAIT_L(0); PG8_BAR; PG8_MMA(0, 0, At, B0); PG8_MMA(0, 1, At, B1); PG8_BAR; PG8_SCHED;
;             PG8_LDA(At, 0, 1); PG8_STAGE(PG8_SB(0, 0), b2, voffB); PG8_STAGE(PG8_SB(0, 1), b2 + hstep, voffB); PG8_STAGE(PG8_SA(0, 0), a2, voffA);
;             PG8_WAIT_V(8); PG8_WAIT_L(0); PG8_BAR; PG8_MMA(1, 0, At, B0); PG8_MMA(1, 1, At, B1); PG8_BAR; PG8_SCHED;
.LBB0_1488:
	v_add_u32_e32 v162, s43, v152
	ds_read_b128 v[154:157], v162
	ds_read_b128 v[158:161], v162 offset:1024
	ds_read_b128 v[166:169], v162 offset:2048
	ds_read_b128 v[170:173], v162 offset:3072
	v_add_u32_e32 v162, s44, v152
	s_add_u32 s2, s0, s40
	ds_read_b128 v[174:177], v162
	ds_read_b128 v[178:181], v162 offset:1024
	ds_read_b128 v[182:185], v162 offset:2048
	ds_read_b128 v[186:189], v162 offset:3072
	s_addc_u32 s3, s1, s41
	s_add_u32 s2, s2, 0x100
	s_addc_u32 s3, s3, 0
	s_add_u32 s51, s46, s40
	s_addc_u32 s52, s47, s41
	s_cmpk_eq_i32 s40, 0x700
	s_cselect_b32 s15, s29, s3
	s_cselect_b32 s14, s48, s2
	s_cselect_b32 s3, s25, s52
	s_cselect_b32 s2, s49, s51
	v_lshl_add_u64 v[162:163], v[146:147], 0, s[40:41]
	s_add_i32 m0, s26, 0xc000
	ds_read_b128 v[190:193], v153
	ds_read_b128 v[194:197], v153 offset:1024
	ds_read_b128 v[198:201], v153 offset:2048
	ds_read_b128 v[202:205], v153 offset:3072
	ds_read_b128 v[206:209], v153 offset:4096
	ds_read_b128 v[210:213], v153 offset:5120
	ds_read_b128 v[214:217], v153 offset:6144
	ds_read_b128 v[218:221], v153 offset:7168
	global_load_lds_dwordx4 v[162:163], off
	v_lshl_add_u64 v[162:163], v[148:149], 0, s[40:41]
	s_add_i32 m0, s26, 0xe000
	s_nop 0
	global_load_lds_dwordx4 v[162:163], off
	s_waitcnt vmcnt(8)
	s_waitcnt lgkmcnt(0)
	v_mfma_f32_16x16x32_bf16 v[94:97], v[154:157], v[190:193], v[94:97]
	v_mfma_f32_16x16x32_bf16 v[102:105], v[166:169], v[190:193], v[102:105]
	v_mfma_f32_16x16x32_bf16 v[106:109], v[154:157], v[198:201], v[106:109]
	v_mfma_f32_16x16x32_bf16 v[110:113], v[166:169], v[198:201], v[110:113]
	v_mfma_f32_16x16x32_bf16 v[114:117], v[154:157], v[206:209], v[114:117]
	v_mfma_f32_16x16x32_bf16 v[122:125], v[166:169], v[206:209], v[122:125]
	s_barrier
	s_setprio 1
	s_waitcnt lgkmcnt(0)
	v_mfma_f32_16x16x32_bf16 v[126:129], v[154:157], v[214:217], v[126:129]
	v_mfma_f32_16x16x32_bf16 v[118:121], v[166:169], v[214:217], v[118:121]
	v_mfma_f32_16x16x32_bf16 v[94:97], v[158:161], v[194:197], v[94:97]
	v_mfma_f32_16x16x32_bf16 v[102:105], v[170:173], v[194:197], v[102:105]
	v_mfma_f32_16x16x32_bf16 v[106:109], v[158:161], v[202:205], v[106:109]
	v_mfma_f32_16x16x32_bf16 v[110:113], v[170:173], v[202:205], v[110:113]
	v_mfma_f32_16x16x32_bf16 v[114:117], v[158:161], v[210:213], v[114:117]
	v_mfma_f32_16x16x32_bf16 v[122:125], v[170:173], v[210:213], v[122:125]
	v_mfma_f32_16x16x32_bf16 v[126:129], v[158:161], v[218:221], v[126:129]
	v_mfma_f32_16x16x32_bf16 v[118:121], v[170:173], v[218:221], v[118:121]
	s_setprio 0
	s_setprio 1
	v_mfma_f32_16x16x32_bf16 v[90:93], v[174:177], v[190:193], v[90:93]
	v_mfma_f32_16x16x32_bf16 v[74:77], v[182:185], v[190:193], v[74:77]
	v_mfma_f32_16x16x32_bf16 v[78:81], v[174:177], v[198:201], v[78:81]
	v_mfma_f32_16x16x32_bf16 v[66:69], v[182:185], v[198:201], v[66:69]
	v_mfma_f32_16x16x32_bf16 v[98:101], v[174:177], v[206:209], v[98:101]
	v_mfma_f32_16x16x32_bf16 v[86:89], v[182:185], v[206:209], v[86:89]
	v_mfma_f32_16x16x32_bf16 v[82:85], v[174:177], v[214:217], v[82:85]
	v_mfma_f32_16x16x32_bf16 v[70:73], v[182:185], v[214:217], v[70:73]
	v_mfma_f32_16x16x32_bf16 v[90:93], v[178:181], v[194:197], v[90:93]
	v_mfma_f32_16x16x32_bf16 v[74:77], v[186:189], v[194:197], v[74:77]
	v_mfma_f32_16x16x32_bf16 v[78:81], v[178:181], v[202:205], v[78:81]
	v_mfma_f32_16x16x32_bf16 v[66:69], v[186:189], v[202:205], v[66:69]
	v_mfma_f32_16x16x32_bf16 v[98:101], v[178:181], v[210:213], v[98:101]
	v_mfma_f32_16x16x32_bf16 v[86:89], v[186:189], v[210:213], v[86:89]
	v_mfma_f32_16x16x32_bf16 v[82:85], v[178:181], v[218:221], v[82:85]
	v_mfma_f32_16x16x32_bf16 v[70:73], v[186:189], v[218:221], v[70:73]
	s_setprio 0
	s_barrier
	s_add_i32 s51, s43, s21
	v_lshl_add_u64 v[162:163], s[2:3], 0, v[132:133]
	s_mov_b32 m0, s51
	ds_read_b128 v[190:193], v153 offset:16384
	ds_read_b128 v[194:197], v153 offset:17408
	ds_read_b128 v[198:201], v153 offset:18432
	ds_read_b128 v[202:205], v153 offset:19456
	ds_read_b128 v[206:209], v153 offset:20480
	ds_read_b128 v[210:213], v153 offset:21504
	ds_read_b128 v[214:217], v153 offset:22528
	ds_read_b128 v[218:221], v153 offset:23552
	global_load_lds_dwordx4 v[162:163], off
	s_add_i32 m0, s51, 0x2000
	s_add_u32 s52, s2, 0x40000
	v_lshl_add_u64 v[222:223], s[2:3], 0, v[136:137]
	s_addc_u32 s53, s3, 0
	s_add_i32 s51, s44, s21
	global_load_lds_dwordx4 v[222:223], off
	v_lshl_add_u64 v[224:225], s[52:53], 0, v[132:133]
	s_mov_b32 m0, s51
	v_lshl_add_u64 v[226:227], s[14:15], 0, v[134:135]
	global_load_lds_dwordx4 v[224:225], off
	v_lshl_add_u64 v[224:225], s[52:53], 0, v[136:137]
	s_add_i32 m0, s51, 0x2000
	s_nop 0
	global_load_lds_dwordx4 v[224:225], off
	v_lshl_add_u64 v[224:225], s[14:15], 0, v[130:131]
	s_mov_b32 m0, s26
	s_nop 0
	global_load_lds_dwordx4 v[224:225], off
	s_mov_b32 m0, s27
	s_nop 0
	global_load_lds_dwordx4 v[226:227], off
	s_waitcnt vmcnt(8)
	s_waitcnt lgkmcnt(0)
	v_mfma_f32_16x16x32_bf16 v[62:65], v[154:157], v[190:193], v[62:65]
	v_mfma_f32_16x16x32_bf16 v[58:61], v[166:169], v[190:193], v[58:61]
	v_mfma_f32_16x16x32_bf16 v[46:49], v[154:157], v[198:201], v[46:49]
	v_mfma_f32_16x16x32_bf16 v[42:45], v[166:169], v[198:201], v[42:45]
	v_mfma_f32_16x16x32_bf16 v[30:33], v[154:157], v[206:209], v[30:33]
	v_mfma_f32_16x16x32_bf16 v[26:29], v[166:169], v[206:209], v[26:29]
	s_barrier
; #define PG8_STAGE(bufoff, gbase, voff) do { _Pragma("unroll") for (int _i = 0; _i < 2; ++_i) \
;         __builtin_amdgcn_global_load_lds((const unsigned*)((const char*)(gbase) + (voff)[_i]), (PG8_LAS unsigned*)(lds + (bufoff) + ldsw + _i * 8192), 16, 0, 0); } while (0)
; #define PG8_LDA(dst, b, h) do { _Pragma("unroll") for (int m = 0; m < 4; ++m) _Pragma("unroll") for (int k = 0; k < 2; ++k) dst[m][k] = *(const PG8_LAS bf16x8*)(lds + PG8_SA(b, h) + aoff + m * 2048 + k * 1024); } while (0)
; #define PG8_LDB(dst, b, h) do { _Pragma("unroll") for (int n = 0; n < 2; ++n) _Pragma("unroll") for (int k = 0; k < 2; ++k) dst[n][k] = *(const PG8_LAS bf16x8*)(lds + PG8_SB(b, h) + boff + n * 2048 + k * 1024); } while (0)
; #define PG8_MMA(ai, bj, At, Bt) do { __builtin_amdgcn_s_setprio(1); _Pragma("unroll") for (int m = 0; m < 4; ++m) _Pragma("unroll") for (int n = 0; n < 2; ++n) _Pragma("unroll") for (int k = 0; k < 2; ++k) \
;         acc[ai][bj][m][n] = __builtin_amdgcn_mfma_f32_16x16x32_bf16(Bt[n][k], At[m][k], acc[ai][bj][m][n], 0, 0, 0); __builtin_amdgcn_s_setprio(0); } while (0)
; #define PG8_WAIT_V(n) asm volatile("s_waitcnt vmcnt(" #n ")" ::: "memory")
; #define PG8_WAIT_L(n) asm volatile("s_waitcnt lgkmcnt(" #n ")" ::: "memory")
; #define PG8_BAR __builtin_amdgcn_s_barrier()
; #define PG8_SCHED __builtin_amdgcn_sched_barrier(0)
; template <class Epi, class Sched, bool ALIGN_EPI = false, bool SP2 = false>
; __device__ __forceinline__ void gemm_phase(PG8_LAS unsigned char* lds, const Gemm g, const Sched& S, const Epi& E) {
;     ...
;             PG8_WAIT_V(8); PG8_WAIT_L(0); PG8_BAR; PG8_MMA(1, 0, At, B0); PG8_MMA(1, 1, At, B1); PG8_BAR; PG8_SCHED;
;             PG8_LDB(B0, 1, 0); PG8_LDB(B1, 1, 1); PG8_SCHED; PG8_LDA(At, 1, 0); PG8_STAGE(PG8_SA(0, 1), a2 + hstep, voffA);
;             PG8_WAIT_V(8); PG8_WAIT_L(0); PG8_BAR; PG8_MMA(0, 0, At, B0); PG8_MMA(0, 1, At, B1); PG8_BAR; PG8_SCHED;
	s_setprio 1
	s_waitcnt lgkmcnt(0)
	v_mfma_f32_16x16x32_bf16 v[14:17], v[154:157], v[214:217], v[14:17]
	v_mfma_f32_16x16x32_bf16 v[10:13], v[166:169], v[214:217], v[10:13]
	v_mfma_f32_16x16x32_bf16 v[62:65], v[158:161], v[194:197], v[62:65]
	v_mfma_f32_16x16x32_bf16 v[58:61], v[170:173], v[194:197], v[58:61]
	v_mfma_f32_16x16x32_bf16 v[46:49], v[158:161], v[202:205], v[46:49]
	v_mfma_f32_16x16x32_bf16 v[42:45], v[170:173], v[202:205], v[42:45]
	v_mfma_f32_16x16x32_bf16 v[30:33], v[158:161], v[210:213], v[30:33]
	v_mfma_f32_16x16x32_bf16 v[26:29], v[170:173], v[210:213], v[26:29]
	v_mfma_f32_16x16x32_bf16 v[14:17], v[158:161], v[218:221], v[14:17]
	v_mfma_f32_16x16x32_bf16 v[10:13], v[170:173], v[218:221], v[10:13]
	s_setprio 0
	s_setprio 1
	v_mfma_f32_16x16x32_bf16 v[54:57], v[174:177], v[190:193], v[54:57]
	v_mfma_f32_16x16x32_bf16 v[50:53], v[182:185], v[190:193], v[50:53]
	v_mfma_f32_16x16x32_bf16 v[38:41], v[174:177], v[198:201], v[38:41]
	v_mfma_f32_16x16x32_bf16 v[34:37], v[182:185], v[198:201], v[34:37]
	v_mfma_f32_16x16x32_bf16 v[22:25], v[174:177], v[206:209], v[22:25]
	v_mfma_f32_16x16x32_bf16 v[18:21], v[182:185], v[206:209], v[18:21]
	v_mfma_f32_16x16x32_bf16 v[6:9], v[174:177], v[214:217], v[6:9]
	v_mfma_f32_16x16x32_bf16 v[2:5], v[182:185], v[214:217], v[2:5]
	v_mfma_f32_16x16x32_bf16 v[54:57], v[178:181], v[194:197], v[54:57]
	v_mfma_f32_16x16x32_bf16 v[50:53], v[186:189], v[194:197], v[50:53]
	v_mfma_f32_16x16x32_bf16 v[38:41], v[178:181], v[202:205], v[38:41]
	v_mfma_f32_16x16x32_bf16 v[34:37], v[186:189], v[202:205], v[34:37]
	v_mfma_f32_16x16x32_bf16 v[22:25], v[178:181], v[210:213], v[22:25]
	v_mfma_f32_16x16x32_bf16 v[18:21], v[186:189], v[210:213], v[18:21]
	v_mfma_f32_16x16x32_bf16 v[6:9], v[178:181], v[218:221], v[6:9]
	v_mfma_f32_16x16x32_bf16 v[2:5], v[186:189], v[218:221], v[2:5]
	s_setprio 0
	s_barrier
	s_add_i32 s51, 0, 0x18000
	v_add_u32_e32 v165, s51, v152
	s_add_i32 s52, 0, 0x1c000
	ds_read_b128 v[154:157], v165
	ds_read_b128 v[158:161], v165 offset:1024
	ds_read_b128 v[166:169], v165 offset:2048
	ds_read_b128 v[170:173], v165 offset:3072
	v_add_u32_e32 v165, s52, v152
	ds_read_b128 v[174:177], v165
	ds_read_b128 v[178:181], v165 offset:1024
	ds_read_b128 v[182:185], v165 offset:2048
	ds_read_b128 v[186:189], v165 offset:3072
	s_add_u32 s14, s14, 0x40000
	s_addc_u32 s15, s15, 0
	s_mov_b32 m0, s33
	v_lshl_add_u64 v[228:229], s[14:15], 0, v[130:131]
	ds_read_b128 v[190:193], v153 offset:32768
	ds_read_b128 v[194:197], v153 offset:33792
	ds_read_b128 v[198:201], v153 offset:34816
	ds_read_b128 v[202:205], v153 offset:35840
	ds_read_b128 v[206:209], v153 offset:36864
	ds_read_b128 v[210:213], v153 offset:37888
	ds_read_b128 v[214:217], v153 offset:38912
	ds_read_b128 v[218:221], v153 offset:39936
	global_load_lds_dwordx4 v[228:229], off
	v_lshl_add_u64 v[228:229], s[14:15], 0, v[134:135]
	s_mov_b32 m0, s34
	s_nop 0
	global_load_lds_dwordx4 v[228:229], off
	s_waitcnt vmcnt(8)
	s_waitcnt lgkmcnt(0)
	v_mfma_f32_16x16x32_bf16 v[94:97], v[154:157], v[190:193], v[94:97]
	v_mfma_f32_16x16x32_bf16 v[102:105], v[166:169], v[190:193], v[102:105]
	v_mfma_f32_16x16x32_bf16 v[106:109], v[154:157], v[198:201], v[106:109]
	v_mfma_f32_16x16x32_bf16 v[110:113], v[166:169], v[198:201], v[110:113]
	v_mfma_f32_16x16x32_bf16 v[114:117], v[154:157], v[206:209], v[114:117]
	v_mfma_f32_16x16x32_bf16 v[122:125], v[166:169], v[206:209], v[122:125]
	s_barrier
	s_setprio 1
	s_waitcnt lgkmcnt(0)
	v_mfma_f32_16x16x32_bf16 v[126:129], v[154:157], v[214:217], v[126:129]
	v_mfma_f32_16x16x32_bf16 v[118:121], v[166:169], v[214:217], v[118:121]
	v_mfma_f32_16x16x32_bf16 v[94:97], v[158:161], v[194:197], v[94:97]
	v_mfma_f32_16x16x32_bf16 v[102:105], v[170:173], v[194:197], v[102:105]
	v_mfma_f32_16x16x32_bf16 v[106:109], v[158:161], v[202:205], v[106:109]
	v_mfma_f32_16x16x32_bf16 v[110:113], v[170:173], v[202:205], v[110:113]
	v_mfma_f32_16x16x32_bf16 v[114:117], v[158:161], v[210:213], v[114:117]
	v_mfma_f32_16x16x32_bf16 v[122:125], v[170:173], v[210:213], v[122:125]
	v_mfma_f32_16x16x32_bf16 v[126:129], v[158:161], v[218:221], v[126:129]
	v_mfma_f32_16x16x32_bf16 v[118:121], v[170:173], v[218:221], v[118:121]
	s_setprio 0
	s_setprio 1
	v_mfma_f32_16x16x32_bf16 v[90:93], v[174:177], v[190:193], v[90:93]
	v_mfma_f32_16x16x32_bf16 v[74:77], v[182:185], v[190:193], v[74:77]
	v_mfma_f32_16x16x32_bf16 v[78:81], v[174:177], v[198:201], v[78:81]
	v_mfma_f32_16x16x32_bf16 v[66:69], v[182:185], v[198:201], v[66:69]
	v_mfma_f32_16x16x32_bf16 v[98:101], v[174:177], v[206:209], v[98:101]
	v_mfma_f32_16x16x32_bf16 v[86:89], v[182:185], v[206:209], v[86:89]
	v_mfma_f32_16x16x32_bf16 v[82:85], v[174:177], v[214:217], v[82:85]
	v_mfma_f32_16x16x32_bf16 v[70:73], v[182:185], v[214:217], v[70:73]
	v_mfma_f32_16x16x32_bf16 v[90:93], v[178:181], v[194:197], v[90:93]
	v_mfma_f32_16x16x32_bf16 v[74:77], v[186:189], v[194:197], v[74:77]
	v_mfma_f32_16x16x32_bf16 v[78:81], v[178:181], v[202:205], v[78:81]
	v_mfma_f32_16x16x32_bf16 v[66:69], v[186:189], v[202:205], v[66:69]
	v_mfma_f32_16x16x32_bf16 v[98:101], v[178:181], v[210:213], v[98:101]
	v_mfma_f32_16x16x32_bf16 v[86:89], v[186:189], v[210:213], v[86:89]
	v_mfma_f32_16x16x32_bf16 v[82:85], v[178:181], v[218:221], v[82:85]
	v_mfma_f32_16x16x32_bf16 v[70:73], v[186:189], v[218:221], v[70:73]
	s_setprio 0
	s_barrier
; #define PG8_STAGE(bufoff, gbase, voff) do { _Pragma("unroll") for (int _i = 0; _i < 2; ++_i) \
;         __builtin_amdgcn_global_load_lds((const unsigned*)((const char*)(gbase) + (voff)[_i]), (PG8_LAS unsigned*)(lds + (bufoff) + ldsw + _i * 8192), 16, 0, 0); } while (0)
; #define PG8_LDA(dst, b, h) do { _Pragma("unroll") for (int m = 0; m < 4; ++m) _Pragma("unroll") for (int k = 0; k < 2; ++k) dst[m][k] = *(const PG8_LAS bf16x8*)(lds + PG8_SA(b, h) + aoff + m * 2048 + k * 1024); } while (0)
; #define PG8_MMA(ai, bj, At, Bt) do { __builtin_amdgcn_s_setprio(1); _Pragma("unroll") for (int m = 0; m < 4; ++m) _Pragma("unroll") for (int n = 0; n < 2; ++n) _Pragma("unroll") for (int k = 0; k < 2; ++k) \
;         acc[ai][bj][m][n] = __builtin_amdgcn_mfma_f32_16x16x32_bf16(Bt[n][k], At[m][k], acc[ai][bj][m][n], 0, 0, 0); __builtin_amdgcn_s_setprio(0); } while (0)
; #define PG8_WAIT_V(n) asm volatile("s_waitcnt vmcnt(" #n ")" ::: "memory")
; #define PG8_WAIT_L(n) asm volatile("s_waitcnt lgkmcnt(" #n ")" ::: "memory")
; #define PG8_BAR __builtin_amdgcn_s_barrier()
; #define PG8_SCHED __builtin_amdgcn_sched_barrier(0)
; template <class Epi, class Sched, bool ALIGN_EPI = false, bool SP2 = false>
; __device__ __forceinline__ void gemm_phase(PG8_LAS unsigned char* lds, const Gemm g, const Sched& S, const Epi& E) {
;     ...
;             PG8_LDA(At, 1, 1); PG8_STAGE(PG8_SB(1, 0), b3, voffB); PG8_STAGE(PG8_SB(1, 1), b3 + hstep, voffB); PG8_STAGE(PG8_SA(1, 0), a3, voffA);
;             PG8_WAIT_V(8); PG8_WAIT_L(0); PG8_BAR; PG8_MMA(1, 0, At, B0); PG8_MMA(1, 1, At, B1); PG8_BAR; PG8_SCHED;
;     ...
;         if (!has_next) break;
; #pragma unroll
;         for (int a = 0; a < 2; ++a)
; #pragma unroll
;             for (int b = 0; b < 2; ++b)
; #pragma unroll
;                 for (int m = 0; m < 4; ++m)
; #pragma unroll
;                     for (int n = 0; n < 2; ++n) acc[a][b][m][n] = (f32x4){0.f, 0.f, 0.f, 0.f};
;         cur = nxt; cA = nA; cB = nB; ++ui;
	s_add_i32 s14, s51, s21
	v_lshl_add_u64 v[162:163], v[162:163], 0, s[22:23]
	s_mov_b32 m0, s14
	ds_read_b128 v[190:193], v153 offset:49152
	ds_read_b128 v[194:197], v153 offset:50176
	ds_read_b128 v[198:201], v153 offset:51200
	ds_read_b128 v[202:205], v153 offset:52224
	ds_read_b128 v[206:209], v153 offset:53248
	ds_read_b128 v[210:213], v153 offset:54272
	ds_read_b128 v[214:217], v153 offset:55296
	ds_read_b128 v[218:221], v153 offset:56320
	global_load_lds_dwordx4 v[162:163], off
	s_add_i32 m0, s14, 0x2000
	s_add_u32 s2, s2, 0x40080
	v_lshl_add_u64 v[162:163], v[222:223], 0, s[22:23]
	s_addc_u32 s3, s3, 0
	s_add_i32 s14, s52, s21
	global_load_lds_dwordx4 v[162:163], off
	v_lshl_add_u64 v[162:163], s[2:3], 0, v[132:133]
	s_mov_b32 m0, s14
	s_nop 0
	global_load_lds_dwordx4 v[162:163], off
	v_lshl_add_u64 v[162:163], s[2:3], 0, v[136:137]
	s_add_i32 m0, s14, 0x2000
	s_nop 0
	global_load_lds_dwordx4 v[162:163], off
	v_lshl_add_u64 v[162:163], v[224:225], 0, s[22:23]
	s_mov_b32 m0, s37
	s_nop 0
	global_load_lds_dwordx4 v[162:163], off
	v_lshl_add_u64 v[162:163], v[226:227], 0, s[22:23]
	s_mov_b32 m0, s42
	s_nop 0
	global_load_lds_dwordx4 v[162:163], off
	s_waitcnt vmcnt(8)
	s_waitcnt lgkmcnt(0)
	v_mfma_f32_16x16x32_bf16 v[62:65], v[154:157], v[190:193], v[62:65]
	v_mfma_f32_16x16x32_bf16 v[58:61], v[166:169], v[190:193], v[58:61]
	v_mfma_f32_16x16x32_bf16 v[46:49], v[154:157], v[198:201], v[46:49]
	v_mfma_f32_16x16x32_bf16 v[42:45], v[166:169], v[198:201], v[42:45]
	v_mfma_f32_16x16x32_bf16 v[30:33], v[154:157], v[206:209], v[30:33]
	v_mfma_f32_16x16x32_bf16 v[26:29], v[166:169], v[206:209], v[26:29]
	s_barrier
	s_setprio 1
	s_waitcnt lgkmcnt(0)
	v_mfma_f32_16x16x32_bf16 v[14:17], v[154:157], v[214:217], v[14:17]
	v_mfma_f32_16x16x32_bf16 v[10:13], v[166:169], v[214:217], v[10:13]
	v_mfma_f32_16x16x32_bf16 v[62:65], v[158:161], v[194:197], v[62:65]
	v_mfma_f32_16x16x32_bf16 v[58:61], v[170:173], v[194:197], v[58:61]
	v_mfma_f32_16x16x32_bf16 v[46:49], v[158:161], v[202:205], v[46:49]
	v_mfma_f32_16x16x32_bf16 v[42:45], v[170:173], v[202:205], v[42:45]
	v_mfma_f32_16x16x32_bf16 v[30:33], v[158:161], v[210:213], v[30:33]
	v_mfma_f32_16x16x32_bf16 v[26:29], v[170:173], v[210:213], v[26:29]
	v_mfma_f32_16x16x32_bf16 v[14:17], v[158:161], v[218:221], v[14:17]
	v_mfma_f32_16x16x32_bf16 v[10:13], v[170:173], v[218:221], v[10:13]
	s_setprio 0
	s_setprio 1
	v_mfma_f32_16x16x32_bf16 v[54:57], v[174:177], v[190:193], v[54:57]
	v_mfma_f32_16x16x32_bf16 v[50:53], v[182:185], v[190:193], v[50:53]
	v_mfma_f32_16x16x32_bf16 v[38:41], v[174:177], v[198:201], v[38:41]
	v_mfma_f32_16x16x32_bf16 v[34:37], v[182:185], v[198:201], v[34:37]
	v_mfma_f32_16x16x32_bf16 v[22:25], v[174:177], v[206:209], v[22:25]
	v_mfma_f32_16x16x32_bf16 v[18:21], v[182:185], v[206:209], v[18:21]
	v_mfma_f32_16x16x32_bf16 v[6:9], v[174:177], v[214:217], v[6:9]
	v_mfma_f32_16x16x32_bf16 v[2:5], v[182:185], v[214:217], v[2:5]
	v_mfma_f32_16x16x32_bf16 v[54:57], v[178:181], v[194:197], v[54:57]
	v_mfma_f32_16x16x32_bf16 v[50:53], v[186:189], v[194:197], v[50:53]
	v_mfma_f32_16x16x32_bf16 v[38:41], v[178:181], v[202:205], v[38:41]
	v_mfma_f32_16x16x32_bf16 v[34:37], v[186:189], v[202:205], v[34:37]
	v_mfma_f32_16x16x32_bf16 v[22:25], v[178:181], v[210:213], v[22:25]
	v_mfma_f32_16x16x32_bf16 v[18:21], v[186:189], v[210:213], v[18:21]
	v_mfma_f32_16x16x32_bf16 v[6:9], v[178:181], v[218:221], v[6:9]
	v_mfma_f32_16x16x32_bf16 v[2:5], v[186:189], v[218:221], v[2:5]
	s_setprio 0
	s_barrier
	s_add_i32 s50, s50, 2
	s_add_u32 s40, s40, 0x100
	s_addc_u32 s41, s41, 0
	s_cmp_gt_u32 s50, 13
	s_cbranch_scc0 .LBB0_1488
	s_add_u32 s2, s46, 0xffffff00
	s_addc_u32 s3, s47, -1
	s_andn2_b64 vcc, exec, s[8:9]
	s_cbranch_vccnz .LBB0_1491
	v_mov_b32_e32 v2, 0
	s_mov_b32 s20, s24
	s_mov_b32 s12, s28
	s_mov_b64 s[0:1], s[38:39]
	s_mov_b32 s36, s45
	v_mov_b32_e32 v3, v2
	v_mov_b64_e32 v[4:5], v[2:3]
	v_mov_b64_e32 v[6:7], v[2:3]
	v_mov_b64_e32 v[8:9], v[2:3]
	v_mov_b64_e32 v[18:19], v[2:3]
	v_mov_b64_e32 v[20:21], v[2:3]
	v_mov_b64_e32 v[22:23], v[2:3]
	v_mov_b64_e32 v[24:25], v[2:3]
	v_mov_b64_e32 v[34:35], v[2:3]
	v_mov_b64_e32 v[36:37], v[2:3]
	v_mov_b64_e32 v[38:39], v[2:3]
	v_mov_b64_e32 v[40:41], v[2:3]
	v_mov_b64_e32 v[50:51], v[2:3]
	v_mov_b64_e32 v[52:53], v[2:3]
	v_mov_b64_e32 v[54:55], v[2:3]
	v_mov_b64_e32 v[56:57], v[2:3]
	v_mov_b64_e32 v[10:11], v[2:3]
	v_mov_b64_e32 v[12:13], v[2:3]
	v_mov_b64_e32 v[14:15], v[2:3]
	v_mov_b64_e32 v[16:17], v[2:3]
	v_mov_b64_e32 v[26:27], v[2:3]
	v_mov_b64_e32 v[28:29], v[2:3]
	v_mov_b64_e32 v[30:31], v[2:3]
	v_mov_b64_e32 v[32:33], v[2:3]
	v_mov_b64_e32 v[42:43], v[2:3]
	v_mov_b64_e32 v[44:45], v[2:3]
	v_mov_b64_e32 v[46:47], v[2:3]
	v_mov_b64_e32 v[48:49], v[2:3]
	v_mov_b64_e32 v[58:59], v[2:3]
	v_mov_b64_e32 v[60:61], v[2:3]
	v_mov_b64_e32 v[62:63], v[2:3]
	v_mov_b64_e32 v[64:65], v[2:3]
	v_mov_b64_e32 v[70:71], v[2:3]
	v_mov_b64_e32 v[72:73], v[2:3]
	v_mov_b64_e32 v[82:83], v[2:3]
	v_mov_b64_e32 v[84:85], v[2:3]
	v_mov_b64_e32 v[86:87], v[2:3]
	v_mov_b64_e32 v[88:89], v[2:3]
	v_mov_b64_e32 v[98:99], v[2:3]
	v_mov_b64_e32 v[100:101], v[2:3]
	v_mov_b64_e32 v[66:67], v[2:3]
	v_mov_b64_e32 v[68:69], v[2:3]
	v_mov_b64_e32 v[78:79], v[2:3]
	v_mov_b64_e32 v[80:81], v[2:3]
	v_mov_b64_e32 v[74:75], v[2:3]
	v_mov_b64_e32 v[76:77], v[2:3]
	v_mov_b64_e32 v[90:91], v[2:3]
	v_mov_b64_e32 v[92:93], v[2:3]
	v_mov_b64_e32 v[118:119], v[2:3]
	v_mov_b64_e32 v[120:121], v[2:3]
	v_mov_b64_e32 v[126:127], v[2:3]
	v_mov_b64_e32 v[128:129], v[2:3]
	v_mov_b64_e32 v[122:123], v[2:3]
	v_mov_b64_e32 v[124:125], v[2:3]
	v_mov_b64_e32 v[114:115], v[2:3]
	v_mov_b64_e32 v[116:117], v[2:3]
	v_mov_b64_e32 v[110:111], v[2:3]
	v_mov_b64_e32 v[112:113], v[2:3]
	v_mov_b64_e32 v[106:107], v[2:3]
	v_mov_b64_e32 v[108:109], v[2:3]
	v_mov_b64_e32 v[102:103], v[2:3]
	v_mov_b64_e32 v[104:105], v[2:3]
	v_mov_b64_e32 v[94:95], v[2:3]
	v_mov_b64_e32 v[96:97], v[2:3]
	s_branch .LBB0_1492

; #define PG8_STAGE(bufoff, gbase, voff) do { _Pragma("unroll") for (int _i = 0; _i < 2; ++_i) \
;         __builtin_amdgcn_global_load_lds((const unsigned*)((const char*)(gbase) + (voff)[_i]), (PG8_LAS unsigned*)(lds + (bufoff) + ldsw + _i * 8192), 16, 0, 0); } while (0)
; #define PG8_LDA(dst, b, h) do { _Pragma("unroll") for (int m = 0; m < 4; ++m) _Pragma("unroll") for (int k = 0; k < 2; ++k) dst[m][k] = *(const PG8_LAS bf16x8*)(lds + PG8_SA(b, h) + aoff + m * 2048 + k * 1024); } while (0)
; #define PG8_LDB(dst, b, h) do { _Pragma("unroll") for (int n = 0; n < 2; ++n) _Pragma("unroll") for (int k = 0; k < 2; ++k) dst[n][k] = *(const PG8_LAS bf16x8*)(lds + PG8_SB(b, h) + boff + n * 2048 + k * 1024); } while (0)
; #define PG8_MMA(ai, bj, At, Bt) do { __builtin_amdgcn_s_setprio(1); _Pragma("unroll") for (int m = 0; m < 4; ++m) _Pragma("unroll") for (int n = 0; n < 2; ++n) _Pragma("unroll") for (int k = 0; k < 2; ++k) \
;         acc[ai][bj][m][n] = __builtin_amdgcn_mfma_f32_16x16x32_bf16(Bt[n][k], At[m][k], acc[ai][bj][m][n], 0, 0, 0); __builtin_amdgcn_s_setprio(0); } while (0)
; #define PG8_WAIT_V(n) asm volatile("s_waitcnt vmcnt(" #n ")" ::: "memory")
; #define PG8_WAIT_L(n) asm volatile("s_waitcnt lgkmcnt(" #n ")" ::: "memory")
; template <class Epi, class Sched, bool ALIGN_EPI = false, bool SP2 = false>
; __device__ __forceinline__ void gemm_phase(PG8_LAS unsigned char* lds, const Gemm g, const Sched& S, const Epi& E) {
;     ...
;             const bool last = (t == nt - 2);
;             const char* a1 = cA + (size_t)(t + 1) * kstep;
;             const char* a2 = last ? nA : cA + (size_t)(t + 2) * kstep; const char* b2 = last ? nB : cB + (size_t)(t + 2) * kstep;
;             const char* a3 = a2 + kstep; const char* b3 = b2 + kstep;
;             if (last && has_next) S.a_ready(nxt);
;             if constexpr (SP2) {
;             PG8_LDB(B0, 0, 0); PG8_LDB(B1, 0, 1); PG8_SCHED; PG8_LDA(At, 0, 0); PG8_STAGE(PG8_SA(1, 1), a1 + hstep, voffA);
;             PG8_WAIT_V(8); PG8_WAIT_L(0); PG8_BAR; PG8_MMA(0, 0, At, B0); PG8_MMA(0, 1, At, B1); PG8_BAR; PG8_SCHED;
;             PG8_LDA(At, 0, 1); PG8_STAGE(PG8_SB(0, 0), b2, voffB); PG8_STAGE(PG8_SB(0, 1), b2 + hstep, voffB); PG8_STAGE(PG8_SA(0, 0), a2, voffA);
;             PG8_WAIT_V(8); PG8_WAIT_L(0); PG8_BAR; PG8_MMA(1, 0, At, B0); PG8_MMA(1, 1, At, B1); PG8_BAR; PG8_SCHED;
.LBB0_1628:
	ds_read_b128 v[146:149], v153
	ds_read_b128 v[156:159], v153 offset:1024
	ds_read_b128 v[160:163], v153 offset:2048
	ds_read_b128 v[164:167], v153 offset:3072
	ds_read_b128 v[168:171], v154
	ds_read_b128 v[172:175], v154 offset:1024
	ds_read_b128 v[176:179], v154 offset:2048
	ds_read_b128 v[180:183], v154 offset:3072
	s_add_u32 s2, s36, 0xfffc0080
	s_addc_u32 s3, s37, -1
	s_cmp_eq_u32 s48, 12
	s_cselect_b32 s15, s23, s3
	s_cselect_b32 s14, s46, s2
	s_cselect_b32 s3, s21, s35
	s_cselect_b32 s2, s47, s34
	v_lshl_add_u64 v[216:217], s[36:37], 0, v[138:139]
	s_add_i32 m0, s26, 0xc000
	ds_read_b128 v[184:187], v155
	ds_read_b128 v[188:191], v155 offset:1024
	ds_read_b128 v[192:195], v155 offset:2048
	ds_read_b128 v[196:199], v155 offset:3072
	ds_read_b128 v[200:203], v155 offset:4096
	ds_read_b128 v[204:207], v155 offset:5120
	ds_read_b128 v[208:211], v155 offset:6144
	ds_read_b128 v[212:215], v155 offset:7168
	global_load_lds_dwordx4 v[216:217], off
	v_lshl_add_u64 v[216:217], s[36:37], 0, v[140:141]
	s_add_i32 m0, s26, 0xe000
	s_nop 0
	global_load_lds_dwordx4 v[216:217], off
	s_waitcnt vmcnt(8)
	s_waitcnt lgkmcnt(0)
	v_mfma_f32_16x16x32_bf16 v[126:129], v[146:149], v[184:187], v[126:129]
	v_mfma_f32_16x16x32_bf16 v[122:125], v[160:163], v[184:187], v[122:125]
	v_mfma_f32_16x16x32_bf16 v[110:113], v[146:149], v[192:195], v[110:113]
	v_mfma_f32_16x16x32_bf16 v[106:109], v[160:163], v[192:195], v[106:109]
	v_mfma_f32_16x16x32_bf16 v[94:97], v[146:149], v[200:203], v[94:97]
	v_mfma_f32_16x16x32_bf16 v[90:93], v[160:163], v[200:203], v[90:93]
	s_barrier
	s_setprio 1
	s_waitcnt lgkmcnt(0)
	v_mfma_f32_16x16x32_bf16 v[78:81], v[146:149], v[208:211], v[78:81]
	v_mfma_f32_16x16x32_bf16 v[74:77], v[160:163], v[208:211], v[74:77]
	v_mfma_f32_16x16x32_bf16 v[126:129], v[156:159], v[188:191], v[126:129]
	v_mfma_f32_16x16x32_bf16 v[122:125], v[164:167], v[188:191], v[122:125]
	v_mfma_f32_16x16x32_bf16 v[110:113], v[156:159], v[196:199], v[110:113]
	v_mfma_f32_16x16x32_bf16 v[106:109], v[164:167], v[196:199], v[106:109]
	v_mfma_f32_16x16x32_bf16 v[94:97], v[156:159], v[204:207], v[94:97]
	v_mfma_f32_16x16x32_bf16 v[90:93], v[164:167], v[204:207], v[90:93]
	v_mfma_f32_16x16x32_bf16 v[78:81], v[156:159], v[212:215], v[78:81]
	v_mfma_f32_16x16x32_bf16 v[74:77], v[164:167], v[212:215], v[74:77]
	s_setprio 0
	s_setprio 1
	v_mfma_f32_16x16x32_bf16 v[118:121], v[168:171], v[184:187], v[118:121]
	v_mfma_f32_16x16x32_bf16 v[114:117], v[176:179], v[184:187], v[114:117]
	v_mfma_f32_16x16x32_bf16 v[102:105], v[168:171], v[192:195], v[102:105]
	v_mfma_f32_16x16x32_bf16 v[98:101], v[176:179], v[192:195], v[98:101]
	v_mfma_f32_16x16x32_bf16 v[86:89], v[168:171], v[200:203], v[86:89]
	v_mfma_f32_16x16x32_bf16 v[82:85], v[176:179], v[200:203], v[82:85]
	v_mfma_f32_16x16x32_bf16 v[70:73], v[168:171], v[208:211], v[70:73]
	v_mfma_f32_16x16x32_bf16 v[66:69], v[176:179], v[208:211], v[66:69]
	v_mfma_f32_16x16x32_bf16 v[118:121], v[172:175], v[188:191], v[118:121]
	v_mfma_f32_16x16x32_bf16 v[114:117], v[180:183], v[188:191], v[114:117]
	v_mfma_f32_16x16x32_bf16 v[102:105], v[172:175], v[196:199], v[102:105]
	v_mfma_f32_16x16x32_bf16 v[98:101], v[180:183], v[196:199], v[98:101]
	v_mfma_f32_16x16x32_bf16 v[86:89], v[172:175], v[204:207], v[86:89]
	v_mfma_f32_16x16x32_bf16 v[82:85], v[180:183], v[204:207], v[82:85]
	v_mfma_f32_16x16x32_bf16 v[70:73], v[172:175], v[212:215], v[70:73]
	v_mfma_f32_16x16x32_bf16 v[66:69], v[180:183], v[212:215], v[66:69]
	s_setprio 0
	s_barrier
	s_add_i32 s49, s42, s17
	v_lshl_add_u64 v[216:217], s[2:3], 0, v[132:133]
	s_mov_b32 m0, s49
	ds_read_b128 v[184:187], v155 offset:16384
	ds_read_b128 v[188:191], v155 offset:17408
	ds_read_b128 v[192:195], v155 offset:18432
	ds_read_b128 v[196:199], v155 offset:19456
	ds_read_b128 v[200:203], v155 offset:20480
	ds_read_b128 v[204:207], v155 offset:21504
	ds_read_b128 v[208:211], v155 offset:22528
	ds_read_b128 v[212:215], v155 offset:23552
	global_load_lds_dwordx4 v[216:217], off
	s_add_i32 m0, s49, 0x2000
	s_add_u32 s50, s2, 0x40000
	v_lshl_add_u64 v[218:219], s[2:3], 0, v[136:137]
	s_addc_u32 s51, s3, 0
	s_add_i32 s49, s43, s17
	global_load_lds_dwordx4 v[218:219], off
	v_lshl_add_u64 v[220:221], s[50:51], 0, v[132:133]
	s_mov_b32 m0, s49
	v_lshl_add_u64 v[222:223], s[14:15], 0, v[134:135]
	global_load_lds_dwordx4 v[220:221], off
	v_lshl_add_u64 v[220:221], s[50:51], 0, v[136:137]
	s_add_i32 m0, s49, 0x2000
	s_nop 0
	global_load_lds_dwordx4 v[220:221], off
	v_lshl_add_u64 v[220:221], s[14:15], 0, v[130:131]
	s_mov_b32 m0, s26
	s_nop 0
	global_load_lds_dwordx4 v[220:221], off
	s_mov_b32 m0, s27
	s_nop 0
	global_load_lds_dwordx4 v[222:223], off
	s_waitcnt vmcnt(8)
	s_waitcnt lgkmcnt(0)
	v_mfma_f32_16x16x32_bf16 v[62:65], v[146:149], v[184:187], v[62:65]
	v_mfma_f32_16x16x32_bf16 v[58:61], v[160:163], v[184:187], v[58:61]
	v_mfma_f32_16x16x32_bf16 v[46:49], v[146:149], v[192:195], v[46:49]
	v_mfma_f32_16x16x32_bf16 v[42:45], v[160:163], v[192:195], v[42:45]
	v_mfma_f32_16x16x32_bf16 v[30:33], v[146:149], v[200:203], v[30:33]
	v_mfma_f32_16x16x32_bf16 v[26:29], v[160:163], v[200:203], v[26:29]
	s_barrier
; #define PG8_STAGE(bufoff, gbase, voff) do { _Pragma("unroll") for (int _i = 0; _i < 2; ++_i) \
;         __builtin_amdgcn_global_load_lds((const unsigned*)((const char*)(gbase) + (voff)[_i]), (PG8_LAS unsigned*)(lds + (bufoff) + ldsw + _i * 8192), 16, 0, 0); } while (0)
; #define PG8_LDA(dst, b, h) do { _Pragma("unroll") for (int m = 0; m < 4; ++m) _Pragma("unroll") for (int k = 0; k < 2; ++k) dst[m][k] = *(const PG8_LAS bf16x8*)(lds + PG8_SA(b, h) + aoff + m * 2048 + k * 1024); } while (0)
; #define PG8_LDB(dst, b, h) do { _Pragma("unroll") for (int n = 0; n < 2; ++n) _Pragma("unroll") for (int k = 0; k < 2; ++k) dst[n][k] = *(const PG8_LAS bf16x8*)(lds + PG8_SB(b, h) + boff + n * 2048 + k * 1024); } while (0)
; #define PG8_MMA(ai, bj, At, Bt) do { __builtin_amdgcn_s_setprio(1); _Pragma("unroll") for (int m = 0; m < 4; ++m) _Pragma("unroll") for (int n = 0; n < 2; ++n) _Pragma("unroll") for (int k = 0; k < 2; ++k) \
;         acc[ai][bj][m][n] = __builtin_amdgcn_mfma_f32_16x16x32_bf16(Bt[n][k], At[m][k], acc[ai][bj][m][n], 0, 0, 0); __builtin_amdgcn_s_setprio(0); } while (0)
; #define PG8_WAIT_V(n) asm volatile("s_waitcnt vmcnt(" #n ")" ::: "memory")
; #define PG8_WAIT_L(n) asm volatile("s_waitcnt lgkmcnt(" #n ")" ::: "memory")
; #define PG8_BAR __builtin_amdgcn_s_barrier()
; #define PG8_SCHED __builtin_amdgcn_sched_barrier(0)
; template <class Epi, class Sched, bool ALIGN_EPI = false, bool SP2 = false>
; __device__ __forceinline__ void gemm_phase(PG8_LAS unsigned char* lds, const Gemm g, const Sched& S, const Epi& E) {
;     ...
;             PG8_WAIT_V(8); PG8_WAIT_L(0); PG8_BAR; PG8_MMA(1, 0, At, B0); PG8_MMA(1, 1, At, B1); PG8_BAR; PG8_SCHED;
;             PG8_LDB(B0, 1, 0); PG8_LDB(B1, 1, 1); PG8_SCHED; PG8_LDA(At, 1, 0); PG8_STAGE(PG8_SA(0, 1), a2 + hstep, voffA);
;             PG8_WAIT_V(8); PG8_WAIT_L(0); PG8_BAR; PG8_MMA(0, 0, At, B0); PG8_MMA(0, 1, At, B1); PG8_BAR; PG8_SCHED;
	s_setprio 1
	s_waitcnt lgkmcnt(0)
	v_mfma_f32_16x16x32_bf16 v[14:17], v[146:149], v[208:211], v[14:17]
	v_mfma_f32_16x16x32_bf16 v[10:13], v[160:163], v[208:211], v[10:13]
	v_mfma_f32_16x16x32_bf16 v[62:65], v[156:159], v[188:191], v[62:65]
	v_mfma_f32_16x16x32_bf16 v[58:61], v[164:167], v[188:191], v[58:61]
	v_mfma_f32_16x16x32_bf16 v[46:49], v[156:159], v[196:199], v[46:49]
	v_mfma_f32_16x16x32_bf16 v[42:45], v[164:167], v[196:199], v[42:45]
	v_mfma_f32_16x16x32_bf16 v[30:33], v[156:159], v[204:207], v[30:33]
	v_mfma_f32_16x16x32_bf16 v[26:29], v[164:167], v[204:207], v[26:29]
	v_mfma_f32_16x16x32_bf16 v[14:17], v[156:159], v[212:215], v[14:17]
	v_mfma_f32_16x16x32_bf16 v[10:13], v[164:167], v[212:215], v[10:13]
	s_setprio 0
	s_setprio 1
	v_mfma_f32_16x16x32_bf16 v[54:57], v[168:171], v[184:187], v[54:57]
	v_mfma_f32_16x16x32_bf16 v[50:53], v[176:179], v[184:187], v[50:53]
	v_mfma_f32_16x16x32_bf16 v[38:41], v[168:171], v[192:195], v[38:41]
	v_mfma_f32_16x16x32_bf16 v[34:37], v[176:179], v[192:195], v[34:37]
	v_mfma_f32_16x16x32_bf16 v[22:25], v[168:171], v[200:203], v[22:25]
	v_mfma_f32_16x16x32_bf16 v[18:21], v[176:179], v[200:203], v[18:21]
	v_mfma_f32_16x16x32_bf16 v[6:9], v[168:171], v[208:211], v[6:9]
	v_mfma_f32_16x16x32_bf16 v[2:5], v[176:179], v[208:211], v[2:5]
	v_mfma_f32_16x16x32_bf16 v[54:57], v[172:175], v[188:191], v[54:57]
	v_mfma_f32_16x16x32_bf16 v[50:53], v[180:183], v[188:191], v[50:53]
	v_mfma_f32_16x16x32_bf16 v[38:41], v[172:175], v[196:199], v[38:41]
	v_mfma_f32_16x16x32_bf16 v[34:37], v[180:183], v[196:199], v[34:37]
	v_mfma_f32_16x16x32_bf16 v[22:25], v[172:175], v[204:207], v[22:25]
	v_mfma_f32_16x16x32_bf16 v[18:21], v[180:183], v[204:207], v[18:21]
	v_mfma_f32_16x16x32_bf16 v[6:9], v[172:175], v[212:215], v[6:9]
	v_mfma_f32_16x16x32_bf16 v[2:5], v[180:183], v[212:215], v[2:5]
	s_setprio 0
	s_barrier
	s_add_i32 s49, 0, 0x18000
	s_add_i32 s50, 0, 0x1c000
	v_add_u32_e32 v164, s49, v151
	v_add_u32_e32 v180, s50, v151
	ds_read_b128 v[146:149], v164
	ds_read_b128 v[156:159], v164 offset:1024
	ds_read_b128 v[160:163], v164 offset:2048
	ds_read_b128 v[164:167], v164 offset:3072
	ds_read_b128 v[168:171], v180
	ds_read_b128 v[172:175], v180 offset:1024
	ds_read_b128 v[176:179], v180 offset:2048
	ds_read_b128 v[180:183], v180 offset:3072
	s_add_u32 s14, s14, 0x40000
	s_addc_u32 s15, s15, 0
	s_mov_b32 m0, s31
	v_lshl_add_u64 v[224:225], s[14:15], 0, v[130:131]
	ds_read_b128 v[184:187], v155 offset:32768
	ds_read_b128 v[188:191], v155 offset:33792
	ds_read_b128 v[192:195], v155 offset:34816
	ds_read_b128 v[196:199], v155 offset:35840
	ds_read_b128 v[200:203], v155 offset:36864
	ds_read_b128 v[204:207], v155 offset:37888
	ds_read_b128 v[208:211], v155 offset:38912
	ds_read_b128 v[212:215], v155 offset:39936
	global_load_lds_dwordx4 v[224:225], off
	v_lshl_add_u64 v[224:225], s[14:15], 0, v[134:135]
	s_mov_b32 m0, s33
	s_nop 0
	global_load_lds_dwordx4 v[224:225], off
	s_waitcnt vmcnt(8)
	s_waitcnt lgkmcnt(0)
	v_mfma_f32_16x16x32_bf16 v[126:129], v[146:149], v[184:187], v[126:129]
	v_mfma_f32_16x16x32_bf16 v[122:125], v[160:163], v[184:187], v[122:125]
	v_mfma_f32_16x16x32_bf16 v[110:113], v[146:149], v[192:195], v[110:113]
	v_mfma_f32_16x16x32_bf16 v[106:109], v[160:163], v[192:195], v[106:109]
	v_mfma_f32_16x16x32_bf16 v[94:97], v[146:149], v[200:203], v[94:97]
	v_mfma_f32_16x16x32_bf16 v[90:93], v[160:163], v[200:203], v[90:93]
	s_barrier
	s_setprio 1
	s_waitcnt lgkmcnt(0)
	v_mfma_f32_16x16x32_bf16 v[78:81], v[146:149], v[208:211], v[78:81]
	v_mfma_f32_16x16x32_bf16 v[74:77], v[160:163], v[208:211], v[74:77]
	v_mfma_f32_16x16x32_bf16 v[126:129], v[156:159], v[188:191], v[126:129]
	v_mfma_f32_16x16x32_bf16 v[122:125], v[164:167], v[188:191], v[122:125]
	v_mfma_f32_16x16x32_bf16 v[110:113], v[156:159], v[196:199], v[110:113]
	v_mfma_f32_16x16x32_bf16 v[106:109], v[164:167], v[196:199], v[106:109]
	v_mfma_f32_16x16x32_bf16 v[94:97], v[156:159], v[204:207], v[94:97]
	v_mfma_f32_16x16x32_bf16 v[90:93], v[164:167], v[204:207], v[90:93]
	v_mfma_f32_16x16x32_bf16 v[78:81], v[156:159], v[212:215], v[78:81]
	v_mfma_f32_16x16x32_bf16 v[74:77], v[164:167], v[212:215], v[74:77]
	s_setprio 0
	s_setprio 1
	v_mfma_f32_16x16x32_bf16 v[118:121], v[168:171], v[184:187], v[118:121]
	v_mfma_f32_16x16x32_bf16 v[114:117], v[176:179], v[184:187], v[114:117]
	v_mfma_f32_16x16x32_bf16 v[102:105], v[168:171], v[192:195], v[102:105]
	v_mfma_f32_16x16x32_bf16 v[98:101], v[176:179], v[192:195], v[98:101]
	v_mfma_f32_16x16x32_bf16 v[86:89], v[168:171], v[200:203], v[86:89]
	v_mfma_f32_16x16x32_bf16 v[82:85], v[176:179], v[200:203], v[82:85]
	v_mfma_f32_16x16x32_bf16 v[70:73], v[168:171], v[208:211], v[70:73]
	v_mfma_f32_16x16x32_bf16 v[66:69], v[176:179], v[208:211], v[66:69]
	v_mfma_f32_16x16x32_bf16 v[118:121], v[172:175], v[188:191], v[118:121]
	v_mfma_f32_16x16x32_bf16 v[114:117], v[180:183], v[188:191], v[114:117]
	v_mfma_f32_16x16x32_bf16 v[102:105], v[172:175], v[196:199], v[102:105]
	v_mfma_f32_16x16x32_bf16 v[98:101], v[180:183], v[196:199], v[98:101]
	v_mfma_f32_16x16x32_bf16 v[86:89], v[172:175], v[204:207], v[86:89]
	v_mfma_f32_16x16x32_bf16 v[82:85], v[180:183], v[204:207], v[82:85]
	v_mfma_f32_16x16x32_bf16 v[70:73], v[172:175], v[212:215], v[70:73]
	v_mfma_f32_16x16x32_bf16 v[66:69], v[180:183], v[212:215], v[66:69]
	s_setprio 0
	s_barrier
; #define PG8_STAGE(bufoff, gbase, voff) do { _Pragma("unroll") for (int _i = 0; _i < 2; ++_i) \
;         __builtin_amdgcn_global_load_lds((const unsigned*)((const char*)(gbase) + (voff)[_i]), (PG8_LAS unsigned*)(lds + (bufoff) + ldsw + _i * 8192), 16, 0, 0); } while (0)
; #define PG8_LDA(dst, b, h) do { _Pragma("unroll") for (int m = 0; m < 4; ++m) _Pragma("unroll") for (int k = 0; k < 2; ++k) dst[m][k] = *(const PG8_LAS bf16x8*)(lds + PG8_SA(b, h) + aoff + m * 2048 + k * 1024); } while (0)
; #define PG8_MMA(ai, bj, At, Bt) do { __builtin_amdgcn_s_setprio(1); _Pragma("unroll") for (int m = 0; m < 4; ++m) _Pragma("unroll") for (int n = 0; n < 2; ++n) _Pragma("unroll") for (int k = 0; k < 2; ++k) \
;         acc[ai][bj][m][n] = __builtin_amdgcn_mfma_f32_16x16x32_bf16(Bt[n][k], At[m][k], acc[ai][bj][m][n], 0, 0, 0); __builtin_amdgcn_s_setprio(0); } while (0)
; #define PG8_WAIT_V(n) asm volatile("s_waitcnt vmcnt(" #n ")" ::: "memory")
; #define PG8_WAIT_L(n) asm volatile("s_waitcnt lgkmcnt(" #n ")" ::: "memory")
; #define PG8_BAR __builtin_amdgcn_s_barrier()
; #define PG8_SCHED __builtin_amdgcn_sched_barrier(0)
; template <class Epi, class Sched, bool ALIGN_EPI = false, bool SP2 = false>
; __device__ __forceinline__ void gemm_phase(PG8_LAS unsigned char* lds, const Gemm g, const Sched& S, const Epi& E) {
;     ...
;             PG8_LDA(At, 1, 1); PG8_STAGE(PG8_SB(1, 0), b3, voffB); PG8_STAGE(PG8_SB(1, 1), b3 + hstep, voffB); PG8_STAGE(PG8_SA(1, 0), a3, voffA);
;             PG8_WAIT_V(8); PG8_WAIT_L(0); PG8_BAR; PG8_MMA(1, 0, At, B0); PG8_MMA(1, 1, At, B1); PG8_BAR; PG8_SCHED;
;     ...
;         if constexpr (ALIGN_EPI) { if (wr == 0) PG8_BAR; }
	s_add_i32 s14, s49, s17
	v_lshl_add_u64 v[216:217], v[216:217], 0, s[12:13]
	s_mov_b32 m0, s14
	ds_read_b128 v[184:187], v155 offset:49152
	ds_read_b128 v[188:191], v155 offset:50176
	ds_read_b128 v[192:195], v155 offset:51200
	ds_read_b128 v[196:199], v155 offset:52224
	ds_read_b128 v[200:203], v155 offset:53248
	ds_read_b128 v[204:207], v155 offset:54272
	ds_read_b128 v[208:211], v155 offset:55296
	ds_read_b128 v[212:215], v155 offset:56320
	global_load_lds_dwordx4 v[216:217], off
	s_add_i32 m0, s14, 0x2000
	s_add_u32 s2, s2, 0x40080
	v_lshl_add_u64 v[216:217], v[218:219], 0, s[12:13]
	s_addc_u32 s3, s3, 0
	s_add_i32 s14, s50, s17
	global_load_lds_dwordx4 v[216:217], off
	v_lshl_add_u64 v[216:217], s[2:3], 0, v[132:133]
	s_mov_b32 m0, s14
	s_nop 0
	global_load_lds_dwordx4 v[216:217], off
	v_lshl_add_u64 v[216:217], s[2:3], 0, v[136:137]
	s_add_i32 m0, s14, 0x2000
	s_nop 0
	global_load_lds_dwordx4 v[216:217], off
	v_lshl_add_u64 v[216:217], v[220:221], 0, s[12:13]
	s_mov_b32 m0, s39
	s_nop 0
	global_load_lds_dwordx4 v[216:217], off
	v_lshl_add_u64 v[216:217], v[222:223], 0, s[12:13]
	s_mov_b32 m0, s40
	s_nop 0
	global_load_lds_dwordx4 v[216:217], off
	s_waitcnt vmcnt(8)
	s_waitcnt lgkmcnt(0)
	v_mfma_f32_16x16x32_bf16 v[62:65], v[146:149], v[184:187], v[62:65]
	v_mfma_f32_16x16x32_bf16 v[58:61], v[160:163], v[184:187], v[58:61]
	v_mfma_f32_16x16x32_bf16 v[46:49], v[146:149], v[192:195], v[46:49]
	v_mfma_f32_16x16x32_bf16 v[42:45], v[160:163], v[192:195], v[42:45]
	v_mfma_f32_16x16x32_bf16 v[30:33], v[146:149], v[200:203], v[30:33]
	v_mfma_f32_16x16x32_bf16 v[26:29], v[160:163], v[200:203], v[26:29]
	s_barrier
	s_setprio 1
	s_waitcnt lgkmcnt(0)
	v_mfma_f32_16x16x32_bf16 v[14:17], v[146:149], v[208:211], v[14:17]
	v_mfma_f32_16x16x32_bf16 v[10:13], v[160:163], v[208:211], v[10:13]
	v_mfma_f32_16x16x32_bf16 v[62:65], v[156:159], v[188:191], v[62:65]
	v_mfma_f32_16x16x32_bf16 v[58:61], v[164:167], v[188:191], v[58:61]
	v_mfma_f32_16x16x32_bf16 v[46:49], v[156:159], v[196:199], v[46:49]
	v_mfma_f32_16x16x32_bf16 v[42:45], v[164:167], v[196:199], v[42:45]
	v_mfma_f32_16x16x32_bf16 v[30:33], v[156:159], v[204:207], v[30:33]
	v_mfma_f32_16x16x32_bf16 v[26:29], v[164:167], v[204:207], v[26:29]
	v_mfma_f32_16x16x32_bf16 v[14:17], v[156:159], v[212:215], v[14:17]
	v_mfma_f32_16x16x32_bf16 v[10:13], v[164:167], v[212:215], v[10:13]
	s_setprio 0
	s_setprio 1
	v_mfma_f32_16x16x32_bf16 v[54:57], v[168:171], v[184:187], v[54:57]
	v_mfma_f32_16x16x32_bf16 v[50:53], v[176:179], v[184:187], v[50:53]
	v_mfma_f32_16x16x32_bf16 v[38:41], v[168:171], v[192:195], v[38:41]
	v_mfma_f32_16x16x32_bf16 v[34:37], v[176:179], v[192:195], v[34:37]
	v_mfma_f32_16x16x32_bf16 v[22:25], v[168:171], v[200:203], v[22:25]
	v_mfma_f32_16x16x32_bf16 v[18:21], v[176:179], v[200:203], v[18:21]
	v_mfma_f32_16x16x32_bf16 v[6:9], v[168:171], v[208:211], v[6:9]
	v_mfma_f32_16x16x32_bf16 v[2:5], v[176:179], v[208:211], v[2:5]
	v_mfma_f32_16x16x32_bf16 v[54:57], v[172:175], v[188:191], v[54:57]
	v_mfma_f32_16x16x32_bf16 v[50:53], v[180:183], v[188:191], v[50:53]
	v_mfma_f32_16x16x32_bf16 v[38:41], v[172:175], v[196:199], v[38:41]
	v_mfma_f32_16x16x32_bf16 v[34:37], v[180:183], v[196:199], v[34:37]
	v_mfma_f32_16x16x32_bf16 v[22:25], v[172:175], v[204:207], v[22:25]
	v_mfma_f32_16x16x32_bf16 v[18:21], v[180:183], v[204:207], v[18:21]
	v_mfma_f32_16x16x32_bf16 v[6:9], v[172:175], v[212:215], v[6:9]
	v_mfma_f32_16x16x32_bf16 v[2:5], v[180:183], v[212:215], v[2:5]
	s_setprio 0
	s_barrier
	s_add_i32 s48, s48, 2
	s_add_u32 s36, s36, 0x100
	s_addc_u32 s37, s37, 0
	s_add_u32 s34, s34, 0x100
	s_addc_u32 s35, s35, 0
	s_cmp_gt_u32 s48, 13
	s_cbranch_scc0 .LBB0_1628
	s_and_b64 vcc, exec, s[18:19]
	s_cbranch_vccz .LBB0_1631
	s_barrier

; #define PG8_STAGE(bufoff, gbase, voff) do { _Pragma("unroll") for (int _i = 0; _i < 2; ++_i) \
;         __builtin_amdgcn_global_load_lds((const unsigned*)((const char*)(gbase) + (voff)[_i]), (PG8_LAS unsigned*)(lds + (bufoff) + ldsw + _i * 8192), 16, 0, 0); } while (0)
; #define PG8_LDA(dst, b, h) do { _Pragma("unroll") for (int m = 0; m < 4; ++m) _Pragma("unroll") for (int k = 0; k < 2; ++k) dst[m][k] = *(const PG8_LAS bf16x8*)(lds + PG8_SA(b, h) + aoff + m * 2048 + k * 1024); } while (0)
; #define PG8_LDB(dst, b, h) do { _Pragma("unroll") for (int n = 0; n < 2; ++n) _Pragma("unroll") for (int k = 0; k < 2; ++k) dst[n][k] = *(const PG8_LAS bf16x8*)(lds + PG8_SB(b, h) + boff + n * 2048 + k * 1024); } while (0)
; #define PG8_MMA(ai, bj, At, Bt) do { __builtin_amdgcn_s_setprio(1); _Pragma("unroll") for (int m = 0; m < 4; ++m) _Pragma("unroll") for (int n = 0; n < 2; ++n) _Pragma("unroll") for (int k = 0; k < 2; ++k) \
;         acc[ai][bj][m][n] = __builtin_amdgcn_mfma_f32_16x16x32_bf16(Bt[n][k], At[m][k], acc[ai][bj][m][n], 0, 0, 0); __builtin_amdgcn_s_setprio(0); } while (0)
; #define PG8_WAIT_V(n) asm volatile("s_waitcnt vmcnt(" #n ")" ::: "memory")
; #define PG8_WAIT_L(n) asm volatile("s_waitcnt lgkmcnt(" #n ")" ::: "memory")
; #define PG8_BAR __builtin_amdgcn_s_barrier()
; #define PG8_SCHED __builtin_amdgcn_sched_barrier(0)
; template <class Epi, class Sched, bool ALIGN_EPI = false, bool SP2 = false>
; __device__ __forceinline__ void gemm_phase(PG8_LAS unsigned char* lds, const Gemm g, const Sched& S, const Epi& E) {
;     ...
;             PG8_LDB(B0, 0, 0); PG8_LDB(B1, 0, 1); PG8_SCHED; PG8_LDA(At, 0, 0); PG8_STAGE(PG8_SA(1, 1), a1 + hstep, voffA);
;             PG8_WAIT_V(8); PG8_WAIT_L(0); PG8_BAR; PG8_MMA(0, 0, At, B0); PG8_MMA(0, 1, At, B1); PG8_BAR; PG8_SCHED;
;             PG8_LDA(At, 0, 1); PG8_STAGE(PG8_SB(0, 0), b2, voffB); PG8_STAGE(PG8_SB(0, 1), b2 + hstep, voffB); PG8_STAGE(PG8_SA(0, 0), a2, voffA);
;             PG8_WAIT_V(8); PG8_WAIT_L(0); PG8_BAR; PG8_MMA(1, 0, At, B0); PG8_MMA(1, 1, At, B1); PG8_BAR; PG8_SCHED;
.LBB0_1706:
	v_add_u32_e32 v162, s39, v152
	ds_read_b128 v[154:157], v162
	ds_read_b128 v[158:161], v162 offset:1024
	ds_read_b128 v[166:169], v162 offset:2048
	ds_read_b128 v[170:173], v162 offset:3072
	v_add_u32_e32 v162, s40, v152
	s_add_u32 s2, s14, s20
	ds_read_b128 v[174:177], v162
	ds_read_b128 v[178:181], v162 offset:1024
	ds_read_b128 v[182:185], v162 offset:2048
	ds_read_b128 v[186:189], v162 offset:3072
	s_addc_u32 s3, s15, s21
	s_add_u32 s2, s2, 0x100
	s_addc_u32 s3, s3, 0
	s_add_u32 s47, s44, s20
	s_addc_u32 s48, s45, s21
	s_cmpk_eq_i32 s20, 0x1500
	s_cselect_b32 s23, s19, s3
	s_cselect_b32 s22, s18, s2
	s_cselect_b32 s3, s7, s48
	s_cselect_b32 s2, s6, s47
	v_lshl_add_u64 v[162:163], v[146:147], 0, s[20:21]
	s_add_i32 m0, s30, 0xc000
	ds_read_b128 v[190:193], v153
	ds_read_b128 v[194:197], v153 offset:1024
	ds_read_b128 v[198:201], v153 offset:2048
	ds_read_b128 v[202:205], v153 offset:3072
	ds_read_b128 v[206:209], v153 offset:4096
	ds_read_b128 v[210:213], v153 offset:5120
	ds_read_b128 v[214:217], v153 offset:6144
	ds_read_b128 v[218:221], v153 offset:7168
	global_load_lds_dwordx4 v[162:163], off
	v_lshl_add_u64 v[162:163], v[148:149], 0, s[20:21]
	s_add_i32 m0, s30, 0xe000
	s_nop 0
	global_load_lds_dwordx4 v[162:163], off
	s_waitcnt vmcnt(8)
	s_waitcnt lgkmcnt(0)
	v_mfma_f32_16x16x32_bf16 v[70:73], v[154:157], v[190:193], v[70:73]
	v_mfma_f32_16x16x32_bf16 v[78:81], v[166:169], v[190:193], v[78:81]
	v_mfma_f32_16x16x32_bf16 v[94:97], v[154:157], v[198:201], v[94:97]
	v_mfma_f32_16x16x32_bf16 v[118:121], v[166:169], v[198:201], v[118:121]
	v_mfma_f32_16x16x32_bf16 v[106:109], v[154:157], v[206:209], v[106:109]
	v_mfma_f32_16x16x32_bf16 v[114:117], v[166:169], v[206:209], v[114:117]
	s_barrier
	s_setprio 1
	s_waitcnt lgkmcnt(0)
	v_mfma_f32_16x16x32_bf16 v[122:125], v[154:157], v[214:217], v[122:125]
	v_mfma_f32_16x16x32_bf16 v[126:129], v[166:169], v[214:217], v[126:129]
	v_mfma_f32_16x16x32_bf16 v[70:73], v[158:161], v[194:197], v[70:73]
	v_mfma_f32_16x16x32_bf16 v[78:81], v[170:173], v[194:197], v[78:81]
	v_mfma_f32_16x16x32_bf16 v[94:97], v[158:161], v[202:205], v[94:97]
	v_mfma_f32_16x16x32_bf16 v[118:121], v[170:173], v[202:205], v[118:121]
	v_mfma_f32_16x16x32_bf16 v[106:109], v[158:161], v[210:213], v[106:109]
	v_mfma_f32_16x16x32_bf16 v[114:117], v[170:173], v[210:213], v[114:117]
	v_mfma_f32_16x16x32_bf16 v[122:125], v[158:161], v[218:221], v[122:125]
	v_mfma_f32_16x16x32_bf16 v[126:129], v[170:173], v[218:221], v[126:129]
	s_setprio 0
	s_setprio 1
	v_mfma_f32_16x16x32_bf16 v[66:69], v[174:177], v[190:193], v[66:69]
	v_mfma_f32_16x16x32_bf16 v[74:77], v[182:185], v[190:193], v[74:77]
	v_mfma_f32_16x16x32_bf16 v[82:85], v[174:177], v[198:201], v[82:85]
	v_mfma_f32_16x16x32_bf16 v[86:89], v[182:185], v[198:201], v[86:89]
	v_mfma_f32_16x16x32_bf16 v[90:93], v[174:177], v[206:209], v[90:93]
	v_mfma_f32_16x16x32_bf16 v[98:101], v[182:185], v[206:209], v[98:101]
	v_mfma_f32_16x16x32_bf16 v[102:105], v[174:177], v[214:217], v[102:105]
	v_mfma_f32_16x16x32_bf16 v[110:113], v[182:185], v[214:217], v[110:113]
	v_mfma_f32_16x16x32_bf16 v[66:69], v[178:181], v[194:197], v[66:69]
	v_mfma_f32_16x16x32_bf16 v[74:77], v[186:189], v[194:197], v[74:77]
	v_mfma_f32_16x16x32_bf16 v[82:85], v[178:181], v[202:205], v[82:85]
	v_mfma_f32_16x16x32_bf16 v[86:89], v[186:189], v[202:205], v[86:89]
	v_mfma_f32_16x16x32_bf16 v[90:93], v[178:181], v[210:213], v[90:93]
	v_mfma_f32_16x16x32_bf16 v[98:101], v[186:189], v[210:213], v[98:101]
	v_mfma_f32_16x16x32_bf16 v[102:105], v[178:181], v[218:221], v[102:105]
	v_mfma_f32_16x16x32_bf16 v[110:113], v[186:189], v[218:221], v[110:113]
	s_setprio 0
	s_barrier
	s_add_i32 s47, s39, s29
	v_lshl_add_u64 v[162:163], s[2:3], 0, v[132:133]
	s_mov_b32 m0, s47
	ds_read_b128 v[190:193], v153 offset:16384
	ds_read_b128 v[194:197], v153 offset:17408
	ds_read_b128 v[198:201], v153 offset:18432
	ds_read_b128 v[202:205], v153 offset:19456
	ds_read_b128 v[206:209], v153 offset:20480
	ds_read_b128 v[210:213], v153 offset:21504
	ds_read_b128 v[214:217], v153 offset:22528
	ds_read_b128 v[218:221], v153 offset:23552
	global_load_lds_dwordx4 v[162:163], off
	s_add_i32 m0, s47, 0x2000
	s_add_u32 s48, s2, 0xb0000
	v_lshl_add_u64 v[222:223], s[2:3], 0, v[136:137]
	s_addc_u32 s49, s3, 0
	s_add_i32 s47, s40, s29
	global_load_lds_dwordx4 v[222:223], off
	v_lshl_add_u64 v[224:225], s[48:49], 0, v[132:133]
	s_mov_b32 m0, s47
	v_lshl_add_u64 v[226:227], s[22:23], 0, v[134:135]
	global_load_lds_dwordx4 v[224:225], off
	v_lshl_add_u64 v[224:225], s[48:49], 0, v[136:137]
	s_add_i32 m0, s47, 0x2000
	s_nop 0
	global_load_lds_dwordx4 v[224:225], off
	v_lshl_add_u64 v[224:225], s[22:23], 0, v[130:131]
	s_mov_b32 m0, s30
	s_nop 0
	global_load_lds_dwordx4 v[224:225], off
	s_mov_b32 m0, s31
	s_nop 0
	global_load_lds_dwordx4 v[226:227], off
	s_waitcnt vmcnt(8)
	s_waitcnt lgkmcnt(0)
	v_mfma_f32_16x16x32_bf16 v[62:65], v[154:157], v[190:193], v[62:65]
	v_mfma_f32_16x16x32_bf16 v[58:61], v[166:169], v[190:193], v[58:61]
	v_mfma_f32_16x16x32_bf16 v[46:49], v[154:157], v[198:201], v[46:49]
	v_mfma_f32_16x16x32_bf16 v[42:45], v[166:169], v[198:201], v[42:45]
	v_mfma_f32_16x16x32_bf16 v[30:33], v[154:157], v[206:209], v[30:33]
	v_mfma_f32_16x16x32_bf16 v[26:29], v[166:169], v[206:209], v[26:29]
	s_barrier
; #define PG8_STAGE(bufoff, gbase, voff) do { _Pragma("unroll") for (int _i = 0; _i < 2; ++_i) \
;         __builtin_amdgcn_global_load_lds((const unsigned*)((const char*)(gbase) + (voff)[_i]), (PG8_LAS unsigned*)(lds + (bufoff) + ldsw + _i * 8192), 16, 0, 0); } while (0)
; #define PG8_LDA(dst, b, h) do { _Pragma("unroll") for (int m = 0; m < 4; ++m) _Pragma("unroll") for (int k = 0; k < 2; ++k) dst[m][k] = *(const PG8_LAS bf16x8*)(lds + PG8_SA(b, h) + aoff + m * 2048 + k * 1024); } while (0)
; #define PG8_LDB(dst, b, h) do { _Pragma("unroll") for (int n = 0; n < 2; ++n) _Pragma("unroll") for (int k = 0; k < 2; ++k) dst[n][k] = *(const PG8_LAS bf16x8*)(lds + PG8_SB(b, h) + boff + n * 2048 + k * 1024); } while (0)
; #define PG8_MMA(ai, bj, At, Bt) do { __builtin_amdgcn_s_setprio(1); _Pragma("unroll") for (int m = 0; m < 4; ++m) _Pragma("unroll") for (int n = 0; n < 2; ++n) _Pragma("unroll") for (int k = 0; k < 2; ++k) \
;         acc[ai][bj][m][n] = __builtin_amdgcn_mfma_f32_16x16x32_bf16(Bt[n][k], At[m][k], acc[ai][bj][m][n], 0, 0, 0); __builtin_amdgcn_s_setprio(0); } while (0)
; #define PG8_WAIT_V(n) asm volatile("s_waitcnt vmcnt(" #n ")" ::: "memory")
; #define PG8_WAIT_L(n) asm volatile("s_waitcnt lgkmcnt(" #n ")" ::: "memory")
; #define PG8_BAR __builtin_amdgcn_s_barrier()
; #define PG8_SCHED __builtin_amdgcn_sched_barrier(0)
; template <class Epi, class Sched, bool ALIGN_EPI = false, bool SP2 = false>
; __device__ __forceinline__ void gemm_phase(PG8_LAS unsigned char* lds, const Gemm g, const Sched& S, const Epi& E) {
;     ...
;             PG8_WAIT_V(8); PG8_WAIT_L(0); PG8_BAR; PG8_MMA(1, 0, At, B0); PG8_MMA(1, 1, At, B1); PG8_BAR; PG8_SCHED;
;             PG8_LDB(B0, 1, 0); PG8_LDB(B1, 1, 1); PG8_SCHED; PG8_LDA(At, 1, 0); PG8_STAGE(PG8_SA(0, 1), a2 + hstep, voffA);
;             PG8_WAIT_V(8); PG8_WAIT_L(0); PG8_BAR; PG8_MMA(0, 0, At, B0); PG8_MMA(0, 1, At, B1); PG8_BAR; PG8_SCHED;
	s_setprio 1
	s_waitcnt lgkmcnt(0)
	v_mfma_f32_16x16x32_bf16 v[14:17], v[154:157], v[214:217], v[14:17]
	v_mfma_f32_16x16x32_bf16 v[10:13], v[166:169], v[214:217], v[10:13]
	v_mfma_f32_16x16x32_bf16 v[62:65], v[158:161], v[194:197], v[62:65]
	v_mfma_f32_16x16x32_bf16 v[58:61], v[170:173], v[194:197], v[58:61]
	v_mfma_f32_16x16x32_bf16 v[46:49], v[158:161], v[202:205], v[46:49]
	v_mfma_f32_16x16x32_bf16 v[42:45], v[170:173], v[202:205], v[42:45]
	v_mfma_f32_16x16x32_bf16 v[30:33], v[158:161], v[210:213], v[30:33]
	v_mfma_f32_16x16x32_bf16 v[26:29], v[170:173], v[210:213], v[26:29]
	v_mfma_f32_16x16x32_bf16 v[14:17], v[158:161], v[218:221], v[14:17]
	v_mfma_f32_16x16x32_bf16 v[10:13], v[170:173], v[218:221], v[10:13]
	s_setprio 0
	s_setprio 1
	v_mfma_f32_16x16x32_bf16 v[54:57], v[174:177], v[190:193], v[54:57]
	v_mfma_f32_16x16x32_bf16 v[50:53], v[182:185], v[190:193], v[50:53]
	v_mfma_f32_16x16x32_bf16 v[38:41], v[174:177], v[198:201], v[38:41]
	v_mfma_f32_16x16x32_bf16 v[34:37], v[182:185], v[198:201], v[34:37]
	v_mfma_f32_16x16x32_bf16 v[22:25], v[174:177], v[206:209], v[22:25]
	v_mfma_f32_16x16x32_bf16 v[18:21], v[182:185], v[206:209], v[18:21]
	v_mfma_f32_16x16x32_bf16 v[6:9], v[174:177], v[214:217], v[6:9]
	v_mfma_f32_16x16x32_bf16 v[2:5], v[182:185], v[214:217], v[2:5]
	v_mfma_f32_16x16x32_bf16 v[54:57], v[178:181], v[194:197], v[54:57]
	v_mfma_f32_16x16x32_bf16 v[50:53], v[186:189], v[194:197], v[50:53]
	v_mfma_f32_16x16x32_bf16 v[38:41], v[178:181], v[202:205], v[38:41]
	v_mfma_f32_16x16x32_bf16 v[34:37], v[186:189], v[202:205], v[34:37]
	v_mfma_f32_16x16x32_bf16 v[22:25], v[178:181], v[210:213], v[22:25]
	v_mfma_f32_16x16x32_bf16 v[18:21], v[186:189], v[210:213], v[18:21]
	v_mfma_f32_16x16x32_bf16 v[6:9], v[178:181], v[218:221], v[6:9]
	v_mfma_f32_16x16x32_bf16 v[2:5], v[186:189], v[218:221], v[2:5]
	s_setprio 0
	s_barrier
	s_add_i32 s47, 0, 0x18000
	v_add_u32_e32 v165, s47, v152
	s_add_i32 s48, 0, 0x1c000
	ds_read_b128 v[154:157], v165
	ds_read_b128 v[158:161], v165 offset:1024
	ds_read_b128 v[166:169], v165 offset:2048
	ds_read_b128 v[170:173], v165 offset:3072
	v_add_u32_e32 v165, s48, v152
	ds_read_b128 v[174:177], v165
	ds_read_b128 v[178:181], v165 offset:1024
	ds_read_b128 v[182:185], v165 offset:2048
	ds_read_b128 v[186:189], v165 offset:3072
	s_add_u32 s22, s22, 0xb0000
	s_addc_u32 s23, s23, 0
	s_mov_b32 m0, s33
	v_lshl_add_u64 v[228:229], s[22:23], 0, v[130:131]
	ds_read_b128 v[190:193], v153 offset:32768
	ds_read_b128 v[194:197], v153 offset:33792
	ds_read_b128 v[198:201], v153 offset:34816
	ds_read_b128 v[202:205], v153 offset:35840
	ds_read_b128 v[206:209], v153 offset:36864
	ds_read_b128 v[210:213], v153 offset:37888
	ds_read_b128 v[214:217], v153 offset:38912
	ds_read_b128 v[218:221], v153 offset:39936
	global_load_lds_dwordx4 v[228:229], off
	v_lshl_add_u64 v[228:229], s[22:23], 0, v[134:135]
	s_mov_b32 m0, s34
	s_nop 0
	global_load_lds_dwordx4 v[228:229], off
	s_waitcnt vmcnt(8)
	s_waitcnt lgkmcnt(0)
	v_mfma_f32_16x16x32_bf16 v[70:73], v[154:157], v[190:193], v[70:73]
	v_mfma_f32_16x16x32_bf16 v[78:81], v[166:169], v[190:193], v[78:81]
	v_mfma_f32_16x16x32_bf16 v[94:97], v[154:157], v[198:201], v[94:97]
	v_mfma_f32_16x16x32_bf16 v[118:121], v[166:169], v[198:201], v[118:121]
	v_mfma_f32_16x16x32_bf16 v[106:109], v[154:157], v[206:209], v[106:109]
	v_mfma_f32_16x16x32_bf16 v[114:117], v[166:169], v[206:209], v[114:117]
	s_barrier
	s_setprio 1
	s_waitcnt lgkmcnt(0)
	v_mfma_f32_16x16x32_bf16 v[122:125], v[154:157], v[214:217], v[122:125]
	v_mfma_f32_16x16x32_bf16 v[126:129], v[166:169], v[214:217], v[126:129]
	v_mfma_f32_16x16x32_bf16 v[70:73], v[158:161], v[194:197], v[70:73]
	v_mfma_f32_16x16x32_bf16 v[78:81], v[170:173], v[194:197], v[78:81]
	v_mfma_f32_16x16x32_bf16 v[94:97], v[158:161], v[202:205], v[94:97]
	v_mfma_f32_16x16x32_bf16 v[118:121], v[170:173], v[202:205], v[118:121]
	v_mfma_f32_16x16x32_bf16 v[106:109], v[158:161], v[210:213], v[106:109]
	v_mfma_f32_16x16x32_bf16 v[114:117], v[170:173], v[210:213], v[114:117]
	v_mfma_f32_16x16x32_bf16 v[122:125], v[158:161], v[218:221], v[122:125]
	v_mfma_f32_16x16x32_bf16 v[126:129], v[170:173], v[218:221], v[126:129]
	s_setprio 0
	s_setprio 1
	v_mfma_f32_16x16x32_bf16 v[66:69], v[174:177], v[190:193], v[66:69]
	v_mfma_f32_16x16x32_bf16 v[74:77], v[182:185], v[190:193], v[74:77]
	v_mfma_f32_16x16x32_bf16 v[82:85], v[174:177], v[198:201], v[82:85]
	v_mfma_f32_16x16x32_bf16 v[86:89], v[182:185], v[198:201], v[86:89]
	v_mfma_f32_16x16x32_bf16 v[90:93], v[174:177], v[206:209], v[90:93]
	v_mfma_f32_16x16x32_bf16 v[98:101], v[182:185], v[206:209], v[98:101]
	v_mfma_f32_16x16x32_bf16 v[102:105], v[174:177], v[214:217], v[102:105]
	v_mfma_f32_16x16x32_bf16 v[110:113], v[182:185], v[214:217], v[110:113]
	v_mfma_f32_16x16x32_bf16 v[66:69], v[178:181], v[194:197], v[66:69]
	v_mfma_f32_16x16x32_bf16 v[74:77], v[186:189], v[194:197], v[74:77]
	v_mfma_f32_16x16x32_bf16 v[82:85], v[178:181], v[202:205], v[82:85]
	v_mfma_f32_16x16x32_bf16 v[86:89], v[186:189], v[202:205], v[86:89]
	v_mfma_f32_16x16x32_bf16 v[90:93], v[178:181], v[210:213], v[90:93]
	v_mfma_f32_16x16x32_bf16 v[98:101], v[186:189], v[210:213], v[98:101]
	v_mfma_f32_16x16x32_bf16 v[102:105], v[178:181], v[218:221], v[102:105]
	v_mfma_f32_16x16x32_bf16 v[110:113], v[186:189], v[218:221], v[110:113]
	s_setprio 0
	s_barrier
; #define PG8_STAGE(bufoff, gbase, voff) do { _Pragma("unroll") for (int _i = 0; _i < 2; ++_i) \
;         __builtin_amdgcn_global_load_lds((const unsigned*)((const char*)(gbase) + (voff)[_i]), (PG8_LAS unsigned*)(lds + (bufoff) + ldsw + _i * 8192), 16, 0, 0); } while (0)
; #define PG8_LDA(dst, b, h) do { _Pragma("unroll") for (int m = 0; m < 4; ++m) _Pragma("unroll") for (int k = 0; k < 2; ++k) dst[m][k] = *(const PG8_LAS bf16x8*)(lds + PG8_SA(b, h) + aoff + m * 2048 + k * 1024); } while (0)
; #define PG8_MMA(ai, bj, At, Bt) do { __builtin_amdgcn_s_setprio(1); _Pragma("unroll") for (int m = 0; m < 4; ++m) _Pragma("unroll") for (int n = 0; n < 2; ++n) _Pragma("unroll") for (int k = 0; k < 2; ++k) \
;         acc[ai][bj][m][n] = __builtin_amdgcn_mfma_f32_16x16x32_bf16(Bt[n][k], At[m][k], acc[ai][bj][m][n], 0, 0, 0); __builtin_amdgcn_s_setprio(0); } while (0)
; #define PG8_WAIT_V(n) asm volatile("s_waitcnt vmcnt(" #n ")" ::: "memory")
; #define PG8_WAIT_L(n) asm volatile("s_waitcnt lgkmcnt(" #n ")" ::: "memory")
; #define PG8_BAR __builtin_amdgcn_s_barrier()
; #define PG8_SCHED __builtin_amdgcn_sched_barrier(0)
; template <class Epi, class Sched, bool ALIGN_EPI = false, bool SP2 = false>
; __device__ __forceinline__ void gemm_phase(PG8_LAS unsigned char* lds, const Gemm g, const Sched& S, const Epi& E) {
;     ...
;             PG8_LDA(At, 1, 1); PG8_STAGE(PG8_SB(1, 0), b3, voffB); PG8_STAGE(PG8_SB(1, 1), b3 + hstep, voffB); PG8_STAGE(PG8_SA(1, 0), a3, voffA);
;             PG8_WAIT_V(8); PG8_WAIT_L(0); PG8_BAR; PG8_MMA(1, 0, At, B0); PG8_MMA(1, 1, At, B1); PG8_BAR; PG8_SCHED;
;     ...
;         if (!has_next) break;
; #pragma unroll
;         for (int a = 0; a < 2; ++a)
; #pragma unroll
;             for (int b = 0; b < 2; ++b)
; #pragma unroll
;                 for (int m = 0; m < 4; ++m)
; #pragma unroll
;                     for (int n = 0; n < 2; ++n) acc[a][b][m][n] = (f32x4){0.f, 0.f, 0.f, 0.f};
;         cur = nxt; cA = nA; cB = nB; ++ui;
	s_add_i32 s22, s47, s29
	v_lshl_add_u64 v[162:163], v[162:163], 0, s[16:17]
	s_mov_b32 m0, s22
	ds_read_b128 v[190:193], v153 offset:49152
	ds_read_b128 v[194:197], v153 offset:50176
	ds_read_b128 v[198:201], v153 offset:51200
	ds_read_b128 v[202:205], v153 offset:52224
	ds_read_b128 v[206:209], v153 offset:53248
	ds_read_b128 v[210:213], v153 offset:54272
	ds_read_b128 v[214:217], v153 offset:55296
	ds_read_b128 v[218:221], v153 offset:56320
	global_load_lds_dwordx4 v[162:163], off
	s_add_i32 m0, s22, 0x2000
	s_add_u32 s2, s2, 0xb0080
	v_lshl_add_u64 v[162:163], v[222:223], 0, s[16:17]
	s_addc_u32 s3, s3, 0
	s_add_i32 s22, s48, s29
	global_load_lds_dwordx4 v[162:163], off
	v_lshl_add_u64 v[162:163], s[2:3], 0, v[132:133]
	s_mov_b32 m0, s22
	s_nop 0
	global_load_lds_dwordx4 v[162:163], off
	v_lshl_add_u64 v[162:163], s[2:3], 0, v[136:137]
	s_add_i32 m0, s22, 0x2000
	s_nop 0
	global_load_lds_dwordx4 v[162:163], off
	v_lshl_add_u64 v[162:163], v[224:225], 0, s[16:17]
	s_mov_b32 m0, s37
	s_nop 0
	global_load_lds_dwordx4 v[162:163], off
	v_lshl_add_u64 v[162:163], v[226:227], 0, s[16:17]
	s_mov_b32 m0, s38
	s_nop 0
	global_load_lds_dwordx4 v[162:163], off
	s_waitcnt vmcnt(8)
	s_waitcnt lgkmcnt(0)
	v_mfma_f32_16x16x32_bf16 v[62:65], v[154:157], v[190:193], v[62:65]
	v_mfma_f32_16x16x32_bf16 v[58:61], v[166:169], v[190:193], v[58:61]
	v_mfma_f32_16x16x32_bf16 v[46:49], v[154:157], v[198:201], v[46:49]
	v_mfma_f32_16x16x32_bf16 v[42:45], v[166:169], v[198:201], v[42:45]
	v_mfma_f32_16x16x32_bf16 v[30:33], v[154:157], v[206:209], v[30:33]
	v_mfma_f32_16x16x32_bf16 v[26:29], v[166:169], v[206:209], v[26:29]
	s_barrier
	s_setprio 1
	s_waitcnt lgkmcnt(0)
	v_mfma_f32_16x16x32_bf16 v[14:17], v[154:157], v[214:217], v[14:17]
	v_mfma_f32_16x16x32_bf16 v[10:13], v[166:169], v[214:217], v[10:13]
	v_mfma_f32_16x16x32_bf16 v[62:65], v[158:161], v[194:197], v[62:65]
	v_mfma_f32_16x16x32_bf16 v[58:61], v[170:173], v[194:197], v[58:61]
	v_mfma_f32_16x16x32_bf16 v[46:49], v[158:161], v[202:205], v[46:49]
	v_mfma_f32_16x16x32_bf16 v[42:45], v[170:173], v[202:205], v[42:45]
	v_mfma_f32_16x16x32_bf16 v[30:33], v[158:161], v[210:213], v[30:33]
	v_mfma_f32_16x16x32_bf16 v[26:29], v[170:173], v[210:213], v[26:29]
	v_mfma_f32_16x16x32_bf16 v[14:17], v[158:161], v[218:221], v[14:17]
	v_mfma_f32_16x16x32_bf16 v[10:13], v[170:173], v[218:221], v[10:13]
	s_setprio 0
	s_setprio 1
	v_mfma_f32_16x16x32_bf16 v[54:57], v[174:177], v[190:193], v[54:57]
	v_mfma_f32_16x16x32_bf16 v[50:53], v[182:185], v[190:193], v[50:53]
	v_mfma_f32_16x16x32_bf16 v[38:41], v[174:177], v[198:201], v[38:41]
	v_mfma_f32_16x16x32_bf16 v[34:37], v[182:185], v[198:201], v[34:37]
	v_mfma_f32_16x16x32_bf16 v[22:25], v[174:177], v[206:209], v[22:25]
	v_mfma_f32_16x16x32_bf16 v[18:21], v[182:185], v[206:209], v[18:21]
	v_mfma_f32_16x16x32_bf16 v[6:9], v[174:177], v[214:217], v[6:9]
	v_mfma_f32_16x16x32_bf16 v[2:5], v[182:185], v[214:217], v[2:5]
	v_mfma_f32_16x16x32_bf16 v[54:57], v[178:181], v[194:197], v[54:57]
	v_mfma_f32_16x16x32_bf16 v[50:53], v[186:189], v[194:197], v[50:53]
	v_mfma_f32_16x16x32_bf16 v[38:41], v[178:181], v[202:205], v[38:41]
	v_mfma_f32_16x16x32_bf16 v[34:37], v[186:189], v[202:205], v[34:37]
	v_mfma_f32_16x16x32_bf16 v[22:25], v[178:181], v[210:213], v[22:25]
	v_mfma_f32_16x16x32_bf16 v[18:21], v[186:189], v[210:213], v[18:21]
	v_mfma_f32_16x16x32_bf16 v[6:9], v[178:181], v[218:221], v[6:9]
	v_mfma_f32_16x16x32_bf16 v[2:5], v[186:189], v[218:221], v[2:5]
	s_setprio 0
	s_barrier
	s_add_i32 s46, s46, 2
	s_add_u32 s20, s20, 0x100
	s_addc_u32 s21, s21, 0
	s_cmp_gt_u32 s46, 41
	s_cbranch_scc0 .LBB0_1706
	s_add_u32 s2, s44, 0xffffff00
	s_addc_u32 s3, s45, -1
	s_and_b64 vcc, exec, s[4:5]
	s_cbranch_vccnz .LBB0_1709
	v_mov_b32_e32 v2, 0
	s_mov_b32 s12, s41
	s_mov_b32 s25, s42
	s_mov_b64 s[14:15], s[18:19]
	s_mov_b32 s36, s43
	v_mov_b32_e32 v3, v2
	v_mov_b64_e32 v[4:5], v[2:3]
	v_mov_b64_e32 v[6:7], v[2:3]
	v_mov_b64_e32 v[8:9], v[2:3]
	v_mov_b64_e32 v[18:19], v[2:3]
	v_mov_b64_e32 v[20:21], v[2:3]
	v_mov_b64_e32 v[22:23], v[2:3]
	v_mov_b64_e32 v[24:25], v[2:3]
	v_mov_b64_e32 v[34:35], v[2:3]
	v_mov_b64_e32 v[36:37], v[2:3]
	v_mov_b64_e32 v[38:39], v[2:3]
	v_mov_b64_e32 v[40:41], v[2:3]
	v_mov_b64_e32 v[50:51], v[2:3]
	v_mov_b64_e32 v[52:53], v[2:3]
	v_mov_b64_e32 v[54:55], v[2:3]
	v_mov_b64_e32 v[56:57], v[2:3]
	v_mov_b64_e32 v[10:11], v[2:3]
	v_mov_b64_e32 v[12:13], v[2:3]
	v_mov_b64_e32 v[14:15], v[2:3]
	v_mov_b64_e32 v[16:17], v[2:3]
	v_mov_b64_e32 v[26:27], v[2:3]
	v_mov_b64_e32 v[28:29], v[2:3]
	v_mov_b64_e32 v[30:31], v[2:3]
	v_mov_b64_e32 v[32:33], v[2:3]
	v_mov_b64_e32 v[42:43], v[2:3]
	v_mov_b64_e32 v[44:45], v[2:3]
	v_mov_b64_e32 v[46:47], v[2:3]
	v_mov_b64_e32 v[48:49], v[2:3]
	v_mov_b64_e32 v[58:59], v[2:3]
	v_mov_b64_e32 v[60:61], v[2:3]
	v_mov_b64_e32 v[62:63], v[2:3]
	v_mov_b64_e32 v[64:65], v[2:3]
	v_mov_b64_e32 v[110:111], v[2:3]
	v_mov_b64_e32 v[112:113], v[2:3]
	v_mov_b64_e32 v[102:103], v[2:3]
	v_mov_b64_e32 v[104:105], v[2:3]
	v_mov_b64_e32 v[98:99], v[2:3]
	v_mov_b64_e32 v[100:101], v[2:3]
	v_mov_b64_e32 v[90:91], v[2:3]
	v_mov_b64_e32 v[92:93], v[2:3]
	v_mov_b64_e32 v[86:87], v[2:3]
	v_mov_b64_e32 v[88:89], v[2:3]
	v_mov_b64_e32 v[82:83], v[2:3]
	v_mov_b64_e32 v[84:85], v[2:3]
	v_mov_b64_e32 v[74:75], v[2:3]
	v_mov_b64_e32 v[76:77], v[2:3]
	v_mov_b64_e32 v[66:67], v[2:3]
	v_mov_b64_e32 v[68:69], v[2:3]
	v_mov_b64_e32 v[126:127], v[2:3]
	v_mov_b64_e32 v[128:129], v[2:3]
	v_mov_b64_e32 v[122:123], v[2:3]
	v_mov_b64_e32 v[124:125], v[2:3]
	v_mov_b64_e32 v[114:115], v[2:3]
	v_mov_b64_e32 v[116:117], v[2:3]
	v_mov_b64_e32 v[106:107], v[2:3]
	v_mov_b64_e32 v[108:109], v[2:3]
	v_mov_b64_e32 v[118:119], v[2:3]
	v_mov_b64_e32 v[120:121], v[2:3]
	v_mov_b64_e32 v[94:95], v[2:3]
	v_mov_b64_e32 v[96:97], v[2:3]
	v_mov_b64_e32 v[78:79], v[2:3]
	v_mov_b64_e32 v[80:81], v[2:3]
	v_mov_b64_e32 v[70:71], v[2:3]
	v_mov_b64_e32 v[72:73], v[2:3]
	s_andn2_b64 vcc, exec, s[0:1]
	s_cbranch_vccnz .LBB0_1710
	s_branch .LBB0_1711
